# v25 + K-loop LDS-DMA loads in the global saddr form where the address is SGPR base + zero-extended lane offset: 6 of 16 v_lshl_add_u64 per pass removed from the load half
# speedup vs baseline: 1.0100x; 1.0100x over previous
; #define PG8_STAGE(bufoff, gbase, voff) do { _Pragma("unroll") for (int _i = 0; _i < 2; ++_i) \
;         __builtin_amdgcn_global_load_lds((const unsigned*)((const char*)(gbase) + (voff)[_i]), (PG8_LAS unsigned*)(lds + (bufoff) + ldsw + _i * 8192), 16, 0, 0); } while (0)
; #define PG8_LDA(dst, b, h) do { _Pragma("unroll") for (int m = 0; m < 4; ++m) _Pragma("unroll") for (int k = 0; k < 2; ++k) dst[m][k] = *(const PG8_LAS bf16x8*)(lds + PG8_SA(b, h) + aoff + m * 2048 + k * 1024); } while (0)
; #define PG8_LDB(dst, b, h) do { _Pragma("unroll") for (int n = 0; n < 2; ++n) _Pragma("unroll") for (int k = 0; k < 2; ++k) dst[n][k] = *(const PG8_LAS bf16x8*)(lds + PG8_SB(b, h) + boff + n * 2048 + k * 1024); } while (0)
; #define PG8_MMA(ai, bj, At, Bt) do { __builtin_amdgcn_s_setprio(1); _Pragma("unroll") for (int m = 0; m < 4; ++m) _Pragma("unroll") for (int n = 0; n < 2; ++n) _Pragma("unroll") for (int k = 0; k < 2; ++k) \
;         acc[ai][bj][m][n] = __builtin_amdgcn_mfma_f32_16x16x32_bf16(Bt[n][k], At[m][k], acc[ai][bj][m][n], 0, 0, 0); __builtin_amdgcn_s_setprio(0); } while (0)
; #define PG8_WAIT_V(n) asm volatile("s_waitcnt vmcnt(" #n ")" ::: "memory")
; #define PG8_WAIT_L(n) asm volatile("s_waitcnt lgkmcnt(" #n ")" ::: "memory")
; template <class Epi, class Sched, bool ALIGN_EPI = false, bool SP2 = false>
; __device__ __forceinline__ void gemm_phase(PG8_LAS unsigned char* lds, const Gemm g, const Sched& S, const Epi& E) {
;     ...
;             const bool last = (t == nt - 2);
;             const char* a1 = cA + (size_t)(t + 1) * kstep;
;             const char* a2 = last ? nA : cA + (size_t)(t + 2) * kstep; const char* b2 = last ? nB : cB + (size_t)(t + 2) * kstep;
;             const char* a3 = a2 + kstep; const char* b3 = b2 + kstep;
;             if (last && has_next) S.a_ready(nxt);
;             if constexpr (SP2) {
;             PG8_LDB(B0, 0, 0); PG8_LDB(B1, 0, 1); PG8_SCHED; PG8_LDA(At, 0, 0); PG8_STAGE(PG8_SA(1, 1), a1 + hstep, voffA);
;             PG8_WAIT_V(8); PG8_WAIT_L(0); PG8_BAR; PG8_MMA(0, 0, At, B0); PG8_MMA(0, 1, At, B1); PG8_BAR; PG8_SCHED;
;             PG8_LDA(At, 0, 1); PG8_STAGE(PG8_SB(0, 0), b2, voffB); PG8_STAGE(PG8_SB(0, 1), b2 + hstepB, voffB); PG8_STAGE(PG8_SA(0, 0), a2, voffA);
;             PG8_WAIT_V(8); PG8_WAIT_L(0); PG8_BAR; PG8_MMA(1, 0, At, B0); PG8_MMA(1, 1, At, B1); PG8_BAR; PG8_SCHED;
.LBB0_192:
	ds_read_b128 v[146:149], v152
	ds_read_b128 v[156:159], v152 offset:1024
	ds_read_b128 v[160:163], v152 offset:2048
	ds_read_b128 v[164:167], v152 offset:3072
	ds_read_b128 v[168:171], v153
	ds_read_b128 v[172:175], v153 offset:1024
	ds_read_b128 v[176:179], v153 offset:2048
	ds_read_b128 v[180:183], v153 offset:3072
	s_add_u32 s22, s20, 0xfffc0080
	s_addc_u32 s23, s21, -1
	s_cmp_eq_u32 s75, 12
	s_cselect_b32 s25, s5, s23
	s_cselect_b32 s24, s13, s22
	s_cselect_b32 s23, s11, s74
	s_cselect_b32 s22, s19, s73
	v_lshl_add_u64 v[216:217], s[20:21], 0, v[138:139]
	s_add_i32 m0, s27, 0xc000
	ds_read_b128 v[184:187], v154
	ds_read_b128 v[188:191], v154 offset:1024
	ds_read_b128 v[192:195], v154 offset:2048
	ds_read_b128 v[196:199], v154 offset:3072
	ds_read_b128 v[200:203], v154 offset:4096
	ds_read_b128 v[204:207], v154 offset:5120
	ds_read_b128 v[208:211], v154 offset:6144
	ds_read_b128 v[212:215], v154 offset:7168
	global_load_lds_dwordx4 v[216:217], off
	v_lshl_add_u64 v[216:217], s[20:21], 0, v[140:141]
	s_add_i32 m0, s27, 0xe000
	s_nop 0
	global_load_lds_dwordx4 v[216:217], off
	s_waitcnt vmcnt(8)
	s_waitcnt lgkmcnt(0)
	s_barrier
	v_mfma_f32_16x16x32_bf16 v[126:129], v[146:149], v[184:187], v[126:129]
	v_mfma_f32_16x16x32_bf16 v[122:125], v[160:163], v[184:187], v[122:125]
	v_mfma_f32_16x16x32_bf16 v[114:117], v[146:149], v[192:195], v[114:117]
	v_mfma_f32_16x16x32_bf16 v[106:109], v[160:163], v[192:195], v[106:109]
	v_mfma_f32_16x16x32_bf16 v[98:101], v[146:149], v[200:203], v[98:101]
	v_mfma_f32_16x16x32_bf16 v[90:93], v[160:163], v[200:203], v[90:93]
	v_mfma_f32_16x16x32_bf16 v[82:85], v[146:149], v[208:211], v[82:85]
	v_mfma_f32_16x16x32_bf16 v[74:77], v[160:163], v[208:211], v[74:77]
	v_mfma_f32_16x16x32_bf16 v[126:129], v[156:159], v[188:191], v[126:129]
	v_mfma_f32_16x16x32_bf16 v[122:125], v[164:167], v[188:191], v[122:125]
	v_mfma_f32_16x16x32_bf16 v[114:117], v[156:159], v[196:199], v[114:117]
	v_mfma_f32_16x16x32_bf16 v[106:109], v[164:167], v[196:199], v[106:109]
	v_mfma_f32_16x16x32_bf16 v[98:101], v[156:159], v[204:207], v[98:101]
	v_mfma_f32_16x16x32_bf16 v[90:93], v[164:167], v[204:207], v[90:93]
	v_mfma_f32_16x16x32_bf16 v[82:85], v[156:159], v[212:215], v[82:85]
	v_mfma_f32_16x16x32_bf16 v[74:77], v[164:167], v[212:215], v[74:77]
	v_mfma_f32_16x16x32_bf16 v[118:121], v[168:171], v[184:187], v[118:121]
	v_mfma_f32_16x16x32_bf16 v[110:113], v[176:179], v[184:187], v[110:113]
	v_mfma_f32_16x16x32_bf16 v[102:105], v[168:171], v[192:195], v[102:105]
	v_mfma_f32_16x16x32_bf16 v[94:97], v[176:179], v[192:195], v[94:97]
	v_mfma_f32_16x16x32_bf16 v[86:89], v[168:171], v[200:203], v[86:89]
	v_mfma_f32_16x16x32_bf16 v[78:81], v[176:179], v[200:203], v[78:81]
	v_mfma_f32_16x16x32_bf16 v[70:73], v[168:171], v[208:211], v[70:73]
	v_mfma_f32_16x16x32_bf16 v[66:69], v[176:179], v[208:211], v[66:69]
	v_mfma_f32_16x16x32_bf16 v[118:121], v[172:175], v[188:191], v[118:121]
	v_mfma_f32_16x16x32_bf16 v[110:113], v[180:183], v[188:191], v[110:113]
	v_mfma_f32_16x16x32_bf16 v[102:105], v[172:175], v[196:199], v[102:105]
	v_mfma_f32_16x16x32_bf16 v[94:97], v[180:183], v[196:199], v[94:97]
	v_mfma_f32_16x16x32_bf16 v[86:89], v[172:175], v[204:207], v[86:89]
	v_mfma_f32_16x16x32_bf16 v[78:81], v[180:183], v[204:207], v[78:81]
	v_mfma_f32_16x16x32_bf16 v[70:73], v[172:175], v[212:215], v[70:73]
	v_mfma_f32_16x16x32_bf16 v[66:69], v[180:183], v[212:215], v[66:69]
	s_barrier
	s_add_i32 s76, s69, s26
	v_lshl_add_u64 v[216:217], s[22:23], 0, v[132:133]
	s_mov_b32 m0, s76
	ds_read_b128 v[184:187], v154 offset:16384
	ds_read_b128 v[188:191], v154 offset:17408
	ds_read_b128 v[192:195], v154 offset:18432
	ds_read_b128 v[196:199], v154 offset:19456
	ds_read_b128 v[200:203], v154 offset:20480
	ds_read_b128 v[204:207], v154 offset:21504
	ds_read_b128 v[208:211], v154 offset:22528
	ds_read_b128 v[212:215], v154 offset:23552
	global_load_lds_dwordx4 v132, s[22:23]
	s_add_i32 m0, s76, 0x2000
	s_add_u32 s76, s22, 0x10000
	v_lshl_add_u64 v[218:219], s[22:23], 0, v[136:137]
	s_addc_u32 s77, s23, 0
	s_add_i32 s78, s70, s26
	global_load_lds_dwordx4 v136, s[22:23]
	s_mov_b32 m0, s78
	v_lshl_add_u64 v[222:223], s[24:25], 0, v[134:135]
	global_load_lds_dwordx4 v132, s[76:77]
	s_add_i32 m0, s78, 0x2000
	s_nop 0
	global_load_lds_dwordx4 v136, s[76:77]
	v_lshl_add_u64 v[220:221], s[24:25], 0, v[130:131]
	s_mov_b32 m0, s27
	s_nop 0
	global_load_lds_dwordx4 v130, s[24:25]
	s_mov_b32 m0, s28
	s_nop 0
	global_load_lds_dwordx4 v134, s[24:25]
	s_waitcnt vmcnt(8)
	s_waitcnt lgkmcnt(0)
	s_barrier
; #define PG8_STAGE(bufoff, gbase, voff) do { _Pragma("unroll") for (int _i = 0; _i < 2; ++_i) \
;         __builtin_amdgcn_global_load_lds((const unsigned*)((const char*)(gbase) + (voff)[_i]), (PG8_LAS unsigned*)(lds + (bufoff) + ldsw + _i * 8192), 16, 0, 0); } while (0)
; #define PG8_LDA(dst, b, h) do { _Pragma("unroll") for (int m = 0; m < 4; ++m) _Pragma("unroll") for (int k = 0; k < 2; ++k) dst[m][k] = *(const PG8_LAS bf16x8*)(lds + PG8_SA(b, h) + aoff + m * 2048 + k * 1024); } while (0)
; #define PG8_LDB(dst, b, h) do { _Pragma("unroll") for (int n = 0; n < 2; ++n) _Pragma("unroll") for (int k = 0; k < 2; ++k) dst[n][k] = *(const PG8_LAS bf16x8*)(lds + PG8_SB(b, h) + boff + n * 2048 + k * 1024); } while (0)
; #define PG8_MMA(ai, bj, At, Bt) do { __builtin_amdgcn_s_setprio(1); _Pragma("unroll") for (int m = 0; m < 4; ++m) _Pragma("unroll") for (int n = 0; n < 2; ++n) _Pragma("unroll") for (int k = 0; k < 2; ++k) \
;         acc[ai][bj][m][n] = __builtin_amdgcn_mfma_f32_16x16x32_bf16(Bt[n][k], At[m][k], acc[ai][bj][m][n], 0, 0, 0); __builtin_amdgcn_s_setprio(0); } while (0)
; #define PG8_WAIT_V(n) asm volatile("s_waitcnt vmcnt(" #n ")" ::: "memory")
; #define PG8_WAIT_L(n) asm volatile("s_waitcnt lgkmcnt(" #n ")" ::: "memory")
; #define PG8_BAR __builtin_amdgcn_s_barrier()
; #define PG8_SCHED __builtin_amdgcn_sched_barrier(0)
; template <class Epi, class Sched, bool ALIGN_EPI = false, bool SP2 = false>
; __device__ __forceinline__ void gemm_phase(PG8_LAS unsigned char* lds, const Gemm g, const Sched& S, const Epi& E) {
;     ...
;             PG8_WAIT_V(8); PG8_WAIT_L(0); PG8_BAR; PG8_MMA(1, 0, At, B0); PG8_MMA(1, 1, At, B1); PG8_BAR; PG8_SCHED;
;             PG8_LDB(B0, 1, 0); PG8_LDB(B1, 1, 1); PG8_SCHED; PG8_LDA(At, 1, 0); PG8_STAGE(PG8_SA(0, 1), a2 + hstep, voffA);
;             PG8_WAIT_V(8); PG8_WAIT_L(0); PG8_BAR; PG8_MMA(0, 0, At, B0); PG8_MMA(0, 1, At, B1); PG8_BAR; PG8_SCHED;
	v_mfma_f32_16x16x32_bf16 v[62:65], v[146:149], v[184:187], v[62:65]
	v_mfma_f32_16x16x32_bf16 v[58:61], v[160:163], v[184:187], v[58:61]
	v_mfma_f32_16x16x32_bf16 v[50:53], v[146:149], v[192:195], v[50:53]
	v_mfma_f32_16x16x32_bf16 v[42:45], v[160:163], v[192:195], v[42:45]
	v_mfma_f32_16x16x32_bf16 v[34:37], v[146:149], v[200:203], v[34:37]
	v_mfma_f32_16x16x32_bf16 v[26:29], v[160:163], v[200:203], v[26:29]
	v_mfma_f32_16x16x32_bf16 v[18:21], v[146:149], v[208:211], v[18:21]
	v_mfma_f32_16x16x32_bf16 v[10:13], v[160:163], v[208:211], v[10:13]
	v_mfma_f32_16x16x32_bf16 v[62:65], v[156:159], v[188:191], v[62:65]
	v_mfma_f32_16x16x32_bf16 v[58:61], v[164:167], v[188:191], v[58:61]
	v_mfma_f32_16x16x32_bf16 v[50:53], v[156:159], v[196:199], v[50:53]
	v_mfma_f32_16x16x32_bf16 v[42:45], v[164:167], v[196:199], v[42:45]
	v_mfma_f32_16x16x32_bf16 v[34:37], v[156:159], v[204:207], v[34:37]
	v_mfma_f32_16x16x32_bf16 v[26:29], v[164:167], v[204:207], v[26:29]
	v_mfma_f32_16x16x32_bf16 v[18:21], v[156:159], v[212:215], v[18:21]
	v_mfma_f32_16x16x32_bf16 v[10:13], v[164:167], v[212:215], v[10:13]
	v_mfma_f32_16x16x32_bf16 v[54:57], v[168:171], v[184:187], v[54:57]
	v_mfma_f32_16x16x32_bf16 v[46:49], v[176:179], v[184:187], v[46:49]
	v_mfma_f32_16x16x32_bf16 v[38:41], v[168:171], v[192:195], v[38:41]
	v_mfma_f32_16x16x32_bf16 v[30:33], v[176:179], v[192:195], v[30:33]
	v_mfma_f32_16x16x32_bf16 v[22:25], v[168:171], v[200:203], v[22:25]
	v_mfma_f32_16x16x32_bf16 v[14:17], v[176:179], v[200:203], v[14:17]
	v_mfma_f32_16x16x32_bf16 v[6:9], v[168:171], v[208:211], v[6:9]
	v_mfma_f32_16x16x32_bf16 v[2:5], v[176:179], v[208:211], v[2:5]
	v_mfma_f32_16x16x32_bf16 v[54:57], v[172:175], v[188:191], v[54:57]
	v_mfma_f32_16x16x32_bf16 v[46:49], v[180:183], v[188:191], v[46:49]
	v_mfma_f32_16x16x32_bf16 v[38:41], v[172:175], v[196:199], v[38:41]
	v_mfma_f32_16x16x32_bf16 v[30:33], v[180:183], v[196:199], v[30:33]
	v_mfma_f32_16x16x32_bf16 v[22:25], v[172:175], v[204:207], v[22:25]
	v_mfma_f32_16x16x32_bf16 v[14:17], v[180:183], v[204:207], v[14:17]
	v_mfma_f32_16x16x32_bf16 v[6:9], v[172:175], v[212:215], v[6:9]
	v_mfma_f32_16x16x32_bf16 v[2:5], v[180:183], v[212:215], v[2:5]
	s_barrier
	s_add_i32 s76, 0, 0x18000
	v_add_u32_e32 v155, s76, v150
	s_add_i32 s77, 0, 0x1c000
	ds_read_b128 v[146:149], v155
	ds_read_b128 v[156:159], v155 offset:1024
	ds_read_b128 v[160:163], v155 offset:2048
	ds_read_b128 v[164:167], v155 offset:3072
	v_add_u32_e32 v155, s77, v150
	ds_read_b128 v[168:171], v155
	ds_read_b128 v[172:175], v155 offset:1024
	ds_read_b128 v[176:179], v155 offset:2048
	ds_read_b128 v[180:183], v155 offset:3072
	s_add_u32 s24, s24, 0x40000
	s_addc_u32 s25, s25, 0
	s_mov_b32 m0, s29
	ds_read_b128 v[184:187], v154 offset:32768
	ds_read_b128 v[188:191], v154 offset:33792
	ds_read_b128 v[192:195], v154 offset:34816
	ds_read_b128 v[196:199], v154 offset:35840
	ds_read_b128 v[200:203], v154 offset:36864
	ds_read_b128 v[204:207], v154 offset:37888
	ds_read_b128 v[208:211], v154 offset:38912
	ds_read_b128 v[212:215], v154 offset:39936
	global_load_lds_dwordx4 v130, s[24:25]
	s_mov_b32 m0, s30
	s_nop 0
	global_load_lds_dwordx4 v134, s[24:25]
	s_waitcnt vmcnt(8)
	s_waitcnt lgkmcnt(0)
	s_barrier
	v_mfma_f32_16x16x32_bf16 v[126:129], v[146:149], v[184:187], v[126:129]
	v_mfma_f32_16x16x32_bf16 v[122:125], v[160:163], v[184:187], v[122:125]
	v_mfma_f32_16x16x32_bf16 v[114:117], v[146:149], v[192:195], v[114:117]
	v_mfma_f32_16x16x32_bf16 v[106:109], v[160:163], v[192:195], v[106:109]
	v_mfma_f32_16x16x32_bf16 v[98:101], v[146:149], v[200:203], v[98:101]
	v_mfma_f32_16x16x32_bf16 v[90:93], v[160:163], v[200:203], v[90:93]
	v_mfma_f32_16x16x32_bf16 v[82:85], v[146:149], v[208:211], v[82:85]
	v_mfma_f32_16x16x32_bf16 v[74:77], v[160:163], v[208:211], v[74:77]
	v_mfma_f32_16x16x32_bf16 v[126:129], v[156:159], v[188:191], v[126:129]
	v_mfma_f32_16x16x32_bf16 v[122:125], v[164:167], v[188:191], v[122:125]
	v_mfma_f32_16x16x32_bf16 v[114:117], v[156:159], v[196:199], v[114:117]
	v_mfma_f32_16x16x32_bf16 v[106:109], v[164:167], v[196:199], v[106:109]
	v_mfma_f32_16x16x32_bf16 v[98:101], v[156:159], v[204:207], v[98:101]
	v_mfma_f32_16x16x32_bf16 v[90:93], v[164:167], v[204:207], v[90:93]
	v_mfma_f32_16x16x32_bf16 v[82:85], v[156:159], v[212:215], v[82:85]
	v_mfma_f32_16x16x32_bf16 v[74:77], v[164:167], v[212:215], v[74:77]
	v_mfma_f32_16x16x32_bf16 v[118:121], v[168:171], v[184:187], v[118:121]
	v_mfma_f32_16x16x32_bf16 v[110:113], v[176:179], v[184:187], v[110:113]
	v_mfma_f32_16x16x32_bf16 v[102:105], v[168:171], v[192:195], v[102:105]
	v_mfma_f32_16x16x32_bf16 v[94:97], v[176:179], v[192:195], v[94:97]
	v_mfma_f32_16x16x32_bf16 v[86:89], v[168:171], v[200:203], v[86:89]
	v_mfma_f32_16x16x32_bf16 v[78:81], v[176:179], v[200:203], v[78:81]
	v_mfma_f32_16x16x32_bf16 v[70:73], v[168:171], v[208:211], v[70:73]
	v_mfma_f32_16x16x32_bf16 v[66:69], v[176:179], v[208:211], v[66:69]
	v_mfma_f32_16x16x32_bf16 v[118:121], v[172:175], v[188:191], v[118:121]
	v_mfma_f32_16x16x32_bf16 v[110:113], v[180:183], v[188:191], v[110:113]
	v_mfma_f32_16x16x32_bf16 v[102:105], v[172:175], v[196:199], v[102:105]
	v_mfma_f32_16x16x32_bf16 v[94:97], v[180:183], v[196:199], v[94:97]
	v_mfma_f32_16x16x32_bf16 v[86:89], v[172:175], v[204:207], v[86:89]
	v_mfma_f32_16x16x32_bf16 v[78:81], v[180:183], v[204:207], v[78:81]
	v_mfma_f32_16x16x32_bf16 v[70:73], v[172:175], v[212:215], v[70:73]
	v_mfma_f32_16x16x32_bf16 v[66:69], v[180:183], v[212:215], v[66:69]
	s_barrier
; #define PG8_STAGE(bufoff, gbase, voff) do { _Pragma("unroll") for (int _i = 0; _i < 2; ++_i) \
;         __builtin_amdgcn_global_load_lds((const unsigned*)((const char*)(gbase) + (voff)[_i]), (PG8_LAS unsigned*)(lds + (bufoff) + ldsw + _i * 8192), 16, 0, 0); } while (0)
; #define PG8_LDA(dst, b, h) do { _Pragma("unroll") for (int m = 0; m < 4; ++m) _Pragma("unroll") for (int k = 0; k < 2; ++k) dst[m][k] = *(const PG8_LAS bf16x8*)(lds + PG8_SA(b, h) + aoff + m * 2048 + k * 1024); } while (0)
; #define PG8_MMA(ai, bj, At, Bt) do { __builtin_amdgcn_s_setprio(1); _Pragma("unroll") for (int m = 0; m < 4; ++m) _Pragma("unroll") for (int n = 0; n < 2; ++n) _Pragma("unroll") for (int k = 0; k < 2; ++k) \
;         acc[ai][bj][m][n] = __builtin_amdgcn_mfma_f32_16x16x32_bf16(Bt[n][k], At[m][k], acc[ai][bj][m][n], 0, 0, 0); __builtin_amdgcn_s_setprio(0); } while (0)
; #define PG8_WAIT_V(n) asm volatile("s_waitcnt vmcnt(" #n ")" ::: "memory")
; #define PG8_WAIT_L(n) asm volatile("s_waitcnt lgkmcnt(" #n ")" ::: "memory")
; #define PG8_BAR __builtin_amdgcn_s_barrier()
; #define PG8_SCHED __builtin_amdgcn_sched_barrier(0)
; template <class Epi, class Sched, bool ALIGN_EPI = false, bool SP2 = false>
; __device__ __forceinline__ void gemm_phase(PG8_LAS unsigned char* lds, const Gemm g, const Sched& S, const Epi& E) {
;     ...
;             PG8_LDA(At, 1, 1); PG8_STAGE(PG8_SB(1, 0), b3, voffB); PG8_STAGE(PG8_SB(1, 1), b3 + hstepB, voffB); PG8_STAGE(PG8_SA(1, 0), a3, voffA);
;             PG8_WAIT_V(8); PG8_WAIT_L(0); PG8_BAR; PG8_MMA(1, 0, At, B0); PG8_MMA(1, 1, At, B1); PG8_BAR; PG8_SCHED;
	s_add_i32 s24, s76, s26
	v_lshl_add_u64 v[216:217], v[216:217], 0, s[6:7]
	s_mov_b32 m0, s24
	ds_read_b128 v[184:187], v154 offset:49152
	ds_read_b128 v[188:191], v154 offset:50176
	ds_read_b128 v[192:195], v154 offset:51200
	ds_read_b128 v[196:199], v154 offset:52224
	ds_read_b128 v[200:203], v154 offset:53248
	ds_read_b128 v[204:207], v154 offset:54272
	ds_read_b128 v[208:211], v154 offset:55296
	ds_read_b128 v[212:215], v154 offset:56320
	global_load_lds_dwordx4 v[216:217], off
	s_add_i32 m0, s24, 0x2000
	s_add_u32 s22, s22, 0x10080
	v_lshl_add_u64 v[216:217], v[218:219], 0, s[6:7]
	s_addc_u32 s23, s23, 0
	s_add_i32 s24, s77, s26
	global_load_lds_dwordx4 v[216:217], off
	s_mov_b32 m0, s24
	s_nop 0
	global_load_lds_dwordx4 v132, s[22:23]
	s_add_i32 m0, s24, 0x2000
	s_nop 0
	global_load_lds_dwordx4 v136, s[22:23]
	v_lshl_add_u64 v[216:217], v[220:221], 0, s[6:7]
	s_mov_b32 m0, s33
	s_nop 0
	global_load_lds_dwordx4 v[216:217], off
	v_lshl_add_u64 v[216:217], v[222:223], 0, s[6:7]
	s_mov_b32 m0, s34
	s_nop 0
	global_load_lds_dwordx4 v[216:217], off
	s_waitcnt vmcnt(8)
	s_waitcnt lgkmcnt(0)
	s_barrier
	v_mfma_f32_16x16x32_bf16 v[62:65], v[146:149], v[184:187], v[62:65]
	v_mfma_f32_16x16x32_bf16 v[58:61], v[160:163], v[184:187], v[58:61]
	v_mfma_f32_16x16x32_bf16 v[50:53], v[146:149], v[192:195], v[50:53]
	v_mfma_f32_16x16x32_bf16 v[42:45], v[160:163], v[192:195], v[42:45]
	v_mfma_f32_16x16x32_bf16 v[34:37], v[146:149], v[200:203], v[34:37]
	v_mfma_f32_16x16x32_bf16 v[26:29], v[160:163], v[200:203], v[26:29]
	v_mfma_f32_16x16x32_bf16 v[18:21], v[146:149], v[208:211], v[18:21]
	v_mfma_f32_16x16x32_bf16 v[10:13], v[160:163], v[208:211], v[10:13]
	v_mfma_f32_16x16x32_bf16 v[62:65], v[156:159], v[188:191], v[62:65]
	v_mfma_f32_16x16x32_bf16 v[58:61], v[164:167], v[188:191], v[58:61]
	v_mfma_f32_16x16x32_bf16 v[50:53], v[156:159], v[196:199], v[50:53]
	v_mfma_f32_16x16x32_bf16 v[42:45], v[164:167], v[196:199], v[42:45]
	v_mfma_f32_16x16x32_bf16 v[34:37], v[156:159], v[204:207], v[34:37]
	v_mfma_f32_16x16x32_bf16 v[26:29], v[164:167], v[204:207], v[26:29]
	v_mfma_f32_16x16x32_bf16 v[18:21], v[156:159], v[212:215], v[18:21]
	v_mfma_f32_16x16x32_bf16 v[10:13], v[164:167], v[212:215], v[10:13]
	v_mfma_f32_16x16x32_bf16 v[54:57], v[168:171], v[184:187], v[54:57]
	v_mfma_f32_16x16x32_bf16 v[46:49], v[176:179], v[184:187], v[46:49]
	v_mfma_f32_16x16x32_bf16 v[38:41], v[168:171], v[192:195], v[38:41]
	v_mfma_f32_16x16x32_bf16 v[30:33], v[176:179], v[192:195], v[30:33]
	v_mfma_f32_16x16x32_bf16 v[22:25], v[168:171], v[200:203], v[22:25]
	v_mfma_f32_16x16x32_bf16 v[14:17], v[176:179], v[200:203], v[14:17]
	v_mfma_f32_16x16x32_bf16 v[6:9], v[168:171], v[208:211], v[6:9]
	v_mfma_f32_16x16x32_bf16 v[2:5], v[176:179], v[208:211], v[2:5]
	v_mfma_f32_16x16x32_bf16 v[54:57], v[172:175], v[188:191], v[54:57]
	v_mfma_f32_16x16x32_bf16 v[46:49], v[180:183], v[188:191], v[46:49]
	v_mfma_f32_16x16x32_bf16 v[38:41], v[172:175], v[196:199], v[38:41]
	v_mfma_f32_16x16x32_bf16 v[30:33], v[180:183], v[196:199], v[30:33]
	v_mfma_f32_16x16x32_bf16 v[22:25], v[172:175], v[204:207], v[22:25]
	v_mfma_f32_16x16x32_bf16 v[14:17], v[180:183], v[204:207], v[14:17]
	v_mfma_f32_16x16x32_bf16 v[6:9], v[172:175], v[212:215], v[6:9]
	v_mfma_f32_16x16x32_bf16 v[2:5], v[180:183], v[212:215], v[2:5]
	s_barrier
	s_add_i32 s75, s75, 2
	s_add_u32 s20, s20, 0x100
	s_addc_u32 s21, s21, 0
	s_add_u32 s73, s73, 0x100
	s_addc_u32 s74, s74, 0
	s_cmp_gt_u32 s75, 13
	s_cbranch_scc0 .LBB0_192
	s_and_b64 vcc, exec, s[8:9]
	s_cbranch_vccz .LBB0_195
	s_barrier

; #define PG8_STAGE(bufoff, gbase, voff) do { _Pragma("unroll") for (int _i = 0; _i < 2; ++_i) \
;         __builtin_amdgcn_global_load_lds((const unsigned*)((const char*)(gbase) + (voff)[_i]), (PG8_LAS unsigned*)(lds + (bufoff) + ldsw + _i * 8192), 16, 0, 0); } while (0)
; #define PG8_LDA(dst, b, h) do { _Pragma("unroll") for (int m = 0; m < 4; ++m) _Pragma("unroll") for (int k = 0; k < 2; ++k) dst[m][k] = *(const PG8_LAS bf16x8*)(lds + PG8_SA(b, h) + aoff + m * 2048 + k * 1024); } while (0)
; #define PG8_LDB(dst, b, h) do { _Pragma("unroll") for (int n = 0; n < 2; ++n) _Pragma("unroll") for (int k = 0; k < 2; ++k) dst[n][k] = *(const PG8_LAS bf16x8*)(lds + PG8_SB(b, h) + boff + n * 2048 + k * 1024); } while (0)
; #define PG8_MMA(ai, bj, At, Bt) do { __builtin_amdgcn_s_setprio(1); _Pragma("unroll") for (int m = 0; m < 4; ++m) _Pragma("unroll") for (int n = 0; n < 2; ++n) _Pragma("unroll") for (int k = 0; k < 2; ++k) \
;         acc[ai][bj][m][n] = __builtin_amdgcn_mfma_f32_16x16x32_bf16(Bt[n][k], At[m][k], acc[ai][bj][m][n], 0, 0, 0); __builtin_amdgcn_s_setprio(0); } while (0)
; #define PG8_WAIT_V(n) asm volatile("s_waitcnt vmcnt(" #n ")" ::: "memory")
; #define PG8_WAIT_L(n) asm volatile("s_waitcnt lgkmcnt(" #n ")" ::: "memory")
; #define PG8_BAR __builtin_amdgcn_s_barrier()
; #define PG8_SCHED __builtin_amdgcn_sched_barrier(0)
; template <class Epi, class Sched, bool ALIGN_EPI = false, bool SP2 = false>
; __device__ __forceinline__ void gemm_phase(PG8_LAS unsigned char* lds, const Gemm g, const Sched& S, const Epi& E) {
;     ...
;             const bool last = (t == nt - 2);
;             const char* a1 = cA + (size_t)(t + 1) * kstep;
;             const char* a2 = last ? nA : cA + (size_t)(t + 2) * kstep; const char* b2 = last ? nB : cB + (size_t)(t + 2) * kstep;
;             const char* a3 = a2 + kstep; const char* b3 = b2 + kstep;
;             if (last && has_next) S.a_ready(nxt);
;             if constexpr (SP2) {
;             PG8_LDB(B0, 0, 0); PG8_LDB(B1, 0, 1); PG8_SCHED; PG8_LDA(At, 0, 0); PG8_STAGE(PG8_SA(1, 1), a1 + hstep, voffA);
;             PG8_WAIT_V(8); PG8_WAIT_L(0); PG8_BAR; PG8_MMA(0, 0, At, B0); PG8_MMA(0, 1, At, B1); PG8_BAR; PG8_SCHED;
;             PG8_LDA(At, 0, 1); PG8_STAGE(PG8_SB(0, 0), b2, voffB); PG8_STAGE(PG8_SB(0, 1), b2 + hstepB, voffB); PG8_STAGE(PG8_SA(0, 0), a2, voffA);
.LBB0_1094:
	v_add_u32_e32 v3, s46, v224
	ds_read_b128 v[134:137], v3
	ds_read_b128 v[138:141], v3 offset:1024
	ds_read_b128 v[142:145], v3 offset:2048
	ds_read_b128 v[146:149], v3 offset:3072
	v_add_u32_e32 v3, s47, v224
	s_add_u32 s26, s22, s24
	ds_read_b128 v[150:153], v3
	ds_read_b128 v[154:157], v3 offset:1024
	ds_read_b128 v[158:161], v3 offset:2048
	ds_read_b128 v[162:165], v3 offset:3072
	s_addc_u32 s27, s23, s25
	s_add_u32 s26, s26, 0x100
	s_addc_u32 s27, s27, 0
	s_add_u32 s58, s62, s24
	s_addc_u32 s59, s63, s25
	s_cmpk_eq_i32 s24, 0x700
	s_cselect_b32 s29, s17, s27
	s_cselect_b32 s28, s54, s26
	s_cselect_b32 s27, s56, s59
	s_cselect_b32 s26, s57, s58
	v_lshl_add_u64 v[4:5], v[214:215], 0, s[24:25]
	s_add_i32 m0, s33, 0xc000
	ds_read_b128 v[166:169], v226
	ds_read_b128 v[170:173], v226 offset:1024
	ds_read_b128 v[174:177], v226 offset:2048
	ds_read_b128 v[178:181], v226 offset:3072
	ds_read_b128 v[182:185], v226 offset:4096
	ds_read_b128 v[186:189], v226 offset:5120
	ds_read_b128 v[190:193], v226 offset:6144
	ds_read_b128 v[194:197], v226 offset:7168
	global_load_lds_dwordx4 v[4:5], off
	v_lshl_add_u64 v[4:5], v[216:217], 0, s[24:25]
	s_add_i32 m0, s33, 0xe000
	s_nop 0
	global_load_lds_dwordx4 v[4:5], off
	s_waitcnt vmcnt(8)
	s_waitcnt lgkmcnt(0)
	s_barrier
	v_mfma_f32_16x16x32_bf16 v[130:133], v[134:137], v[166:169], v[130:133]
	v_mfma_f32_16x16x32_bf16 v[126:129], v[142:145], v[166:169], v[126:129]
	v_mfma_f32_16x16x32_bf16 v[114:117], v[134:137], v[174:177], v[114:117]
	v_mfma_f32_16x16x32_bf16 v[110:113], v[142:145], v[174:177], v[110:113]
	v_mfma_f32_16x16x32_bf16 v[98:101], v[134:137], v[182:185], v[98:101]
	v_mfma_f32_16x16x32_bf16 v[94:97], v[142:145], v[182:185], v[94:97]
	v_mfma_f32_16x16x32_bf16 v[82:85], v[134:137], v[190:193], v[82:85]
	v_mfma_f32_16x16x32_bf16 v[78:81], v[142:145], v[190:193], v[78:81]
	v_mfma_f32_16x16x32_bf16 v[130:133], v[138:141], v[170:173], v[130:133]
	v_mfma_f32_16x16x32_bf16 v[126:129], v[146:149], v[170:173], v[126:129]
	v_mfma_f32_16x16x32_bf16 v[114:117], v[138:141], v[178:181], v[114:117]
	v_mfma_f32_16x16x32_bf16 v[110:113], v[146:149], v[178:181], v[110:113]
	v_mfma_f32_16x16x32_bf16 v[98:101], v[138:141], v[186:189], v[98:101]
	v_mfma_f32_16x16x32_bf16 v[94:97], v[146:149], v[186:189], v[94:97]
	v_mfma_f32_16x16x32_bf16 v[82:85], v[138:141], v[194:197], v[82:85]
	v_mfma_f32_16x16x32_bf16 v[78:81], v[146:149], v[194:197], v[78:81]
	v_mfma_f32_16x16x32_bf16 v[122:125], v[150:153], v[166:169], v[122:125]
	v_mfma_f32_16x16x32_bf16 v[118:121], v[158:161], v[166:169], v[118:121]
	v_mfma_f32_16x16x32_bf16 v[106:109], v[150:153], v[174:177], v[106:109]
	v_mfma_f32_16x16x32_bf16 v[102:105], v[158:161], v[174:177], v[102:105]
	v_mfma_f32_16x16x32_bf16 v[90:93], v[150:153], v[182:185], v[90:93]
	v_mfma_f32_16x16x32_bf16 v[86:89], v[158:161], v[182:185], v[86:89]
	v_mfma_f32_16x16x32_bf16 v[74:77], v[150:153], v[190:193], v[74:77]
	v_mfma_f32_16x16x32_bf16 v[70:73], v[158:161], v[190:193], v[70:73]
	v_mfma_f32_16x16x32_bf16 v[122:125], v[154:157], v[170:173], v[122:125]
	v_mfma_f32_16x16x32_bf16 v[118:121], v[162:165], v[170:173], v[118:121]
	v_mfma_f32_16x16x32_bf16 v[106:109], v[154:157], v[178:181], v[106:109]
	v_mfma_f32_16x16x32_bf16 v[102:105], v[162:165], v[178:181], v[102:105]
	v_mfma_f32_16x16x32_bf16 v[90:93], v[154:157], v[186:189], v[90:93]
	v_mfma_f32_16x16x32_bf16 v[86:89], v[162:165], v[186:189], v[86:89]
	v_mfma_f32_16x16x32_bf16 v[74:77], v[154:157], v[194:197], v[74:77]
	v_mfma_f32_16x16x32_bf16 v[70:73], v[162:165], v[194:197], v[70:73]
	s_barrier
	s_add_i32 s58, s46, s31
	v_lshl_add_u64 v[218:219], s[26:27], 0, v[200:201]
	s_mov_b32 m0, s58
	ds_read_b128 v[166:169], v226 offset:16384
	ds_read_b128 v[170:173], v226 offset:17408
	ds_read_b128 v[174:177], v226 offset:18432
	ds_read_b128 v[178:181], v226 offset:19456
	ds_read_b128 v[182:185], v226 offset:20480
	ds_read_b128 v[186:189], v226 offset:21504
	ds_read_b128 v[190:193], v226 offset:22528
	ds_read_b128 v[194:197], v226 offset:23552
	global_load_lds_dwordx4 v200, s[26:27]
	s_add_i32 m0, s58, 0x2000
	s_add_u32 s58, s26, 0x10000
	v_lshl_add_u64 v[220:221], s[26:27], 0, v[204:205]
	s_addc_u32 s59, s27, 0
	s_add_i32 s65, s47, s31
	global_load_lds_dwordx4 v204, s[26:27]
	s_mov_b32 m0, s65
	v_lshl_add_u64 v[228:229], s[28:29], 0, v[198:199]
	global_load_lds_dwordx4 v200, s[58:59]
	s_add_i32 m0, s65, 0x2000
	v_lshl_add_u64 v[230:231], s[28:29], 0, v[202:203]
	global_load_lds_dwordx4 v204, s[58:59]
	s_mov_b32 m0, s33
	s_nop 0
	global_load_lds_dwordx4 v198, s[28:29]
	s_mov_b32 m0, s34
	s_nop 0
	global_load_lds_dwordx4 v202, s[28:29]
	s_waitcnt vmcnt(8)
	s_waitcnt lgkmcnt(0)
	s_barrier
; #define PG8_STAGE(bufoff, gbase, voff) do { _Pragma("unroll") for (int _i = 0; _i < 2; ++_i) \
;         __builtin_amdgcn_global_load_lds((const unsigned*)((const char*)(gbase) + (voff)[_i]), (PG8_LAS unsigned*)(lds + (bufoff) + ldsw + _i * 8192), 16, 0, 0); } while (0)
; #define PG8_LDA(dst, b, h) do { _Pragma("unroll") for (int m = 0; m < 4; ++m) _Pragma("unroll") for (int k = 0; k < 2; ++k) dst[m][k] = *(const PG8_LAS bf16x8*)(lds + PG8_SA(b, h) + aoff + m * 2048 + k * 1024); } while (0)
; #define PG8_LDB(dst, b, h) do { _Pragma("unroll") for (int n = 0; n < 2; ++n) _Pragma("unroll") for (int k = 0; k < 2; ++k) dst[n][k] = *(const PG8_LAS bf16x8*)(lds + PG8_SB(b, h) + boff + n * 2048 + k * 1024); } while (0)
; #define PG8_MMA(ai, bj, At, Bt) do { __builtin_amdgcn_s_setprio(1); _Pragma("unroll") for (int m = 0; m < 4; ++m) _Pragma("unroll") for (int n = 0; n < 2; ++n) _Pragma("unroll") for (int k = 0; k < 2; ++k) \
;         acc[ai][bj][m][n] = __builtin_amdgcn_mfma_f32_16x16x32_bf16(Bt[n][k], At[m][k], acc[ai][bj][m][n], 0, 0, 0); __builtin_amdgcn_s_setprio(0); } while (0)
; #define PG8_WAIT_V(n) asm volatile("s_waitcnt vmcnt(" #n ")" ::: "memory")
; #define PG8_WAIT_L(n) asm volatile("s_waitcnt lgkmcnt(" #n ")" ::: "memory")
; #define PG8_BAR __builtin_amdgcn_s_barrier()
; #define PG8_SCHED __builtin_amdgcn_sched_barrier(0)
; template <class Epi, class Sched, bool ALIGN_EPI = false, bool SP2 = false>
; __device__ __forceinline__ void gemm_phase(PG8_LAS unsigned char* lds, const Gemm g, const Sched& S, const Epi& E) {
;     ...
;             PG8_WAIT_V(8); PG8_WAIT_L(0); PG8_BAR; PG8_MMA(1, 0, At, B0); PG8_MMA(1, 1, At, B1); PG8_BAR; PG8_SCHED;
;             PG8_LDB(B0, 1, 0); PG8_LDB(B1, 1, 1); PG8_SCHED; PG8_LDA(At, 1, 0); PG8_STAGE(PG8_SA(0, 1), a2 + hstep, voffA);
;             PG8_WAIT_V(8); PG8_WAIT_L(0); PG8_BAR; PG8_MMA(0, 0, At, B0); PG8_MMA(0, 1, At, B1); PG8_BAR; PG8_SCHED;
	v_mfma_f32_16x16x32_bf16 v[66:69], v[134:137], v[166:169], v[66:69]
	v_mfma_f32_16x16x32_bf16 v[62:65], v[142:145], v[166:169], v[62:65]
	v_mfma_f32_16x16x32_bf16 v[50:53], v[134:137], v[174:177], v[50:53]
	v_mfma_f32_16x16x32_bf16 v[46:49], v[142:145], v[174:177], v[46:49]
	v_mfma_f32_16x16x32_bf16 v[34:37], v[134:137], v[182:185], v[34:37]
	v_mfma_f32_16x16x32_bf16 v[30:33], v[142:145], v[182:185], v[30:33]
	v_mfma_f32_16x16x32_bf16 v[18:21], v[134:137], v[190:193], v[18:21]
	v_mfma_f32_16x16x32_bf16 v[14:17], v[142:145], v[190:193], v[14:17]
	v_mfma_f32_16x16x32_bf16 v[66:69], v[138:141], v[170:173], v[66:69]
	v_mfma_f32_16x16x32_bf16 v[62:65], v[146:149], v[170:173], v[62:65]
	v_mfma_f32_16x16x32_bf16 v[50:53], v[138:141], v[178:181], v[50:53]
	v_mfma_f32_16x16x32_bf16 v[46:49], v[146:149], v[178:181], v[46:49]
	v_mfma_f32_16x16x32_bf16 v[34:37], v[138:141], v[186:189], v[34:37]
	v_mfma_f32_16x16x32_bf16 v[30:33], v[146:149], v[186:189], v[30:33]
	v_mfma_f32_16x16x32_bf16 v[18:21], v[138:141], v[194:197], v[18:21]
	v_mfma_f32_16x16x32_bf16 v[14:17], v[146:149], v[194:197], v[14:17]
	v_mfma_f32_16x16x32_bf16 v[58:61], v[150:153], v[166:169], v[58:61]
	v_mfma_f32_16x16x32_bf16 v[54:57], v[158:161], v[166:169], v[54:57]
	v_mfma_f32_16x16x32_bf16 v[42:45], v[150:153], v[174:177], v[42:45]
	v_mfma_f32_16x16x32_bf16 v[38:41], v[158:161], v[174:177], v[38:41]
	v_mfma_f32_16x16x32_bf16 v[26:29], v[150:153], v[182:185], v[26:29]
	v_mfma_f32_16x16x32_bf16 v[22:25], v[158:161], v[182:185], v[22:25]
	v_mfma_f32_16x16x32_bf16 v[10:13], v[150:153], v[190:193], v[10:13]
	v_mfma_f32_16x16x32_bf16 v[4:7], v[158:161], v[190:193], v[6:9]
	v_mfma_f32_16x16x32_bf16 v[58:61], v[154:157], v[170:173], v[58:61]
	v_mfma_f32_16x16x32_bf16 v[54:57], v[162:165], v[170:173], v[54:57]
	v_mfma_f32_16x16x32_bf16 v[42:45], v[154:157], v[178:181], v[42:45]
	v_mfma_f32_16x16x32_bf16 v[38:41], v[162:165], v[178:181], v[38:41]
	v_mfma_f32_16x16x32_bf16 v[26:29], v[154:157], v[186:189], v[26:29]
	v_mfma_f32_16x16x32_bf16 v[22:25], v[162:165], v[186:189], v[22:25]
	v_mfma_f32_16x16x32_bf16 v[10:13], v[154:157], v[194:197], v[10:13]
	v_mfma_f32_16x16x32_bf16 v[4:7], v[162:165], v[194:197], v[4:7]
	s_barrier
	s_add_i32 s58, 0, 0x18000
	v_add_u32_e32 v3, s58, v224
	s_add_i32 s59, 0, 0x1c000
	ds_read_b128 v[134:137], v3
	ds_read_b128 v[138:141], v3 offset:1024
	ds_read_b128 v[142:145], v3 offset:2048
	ds_read_b128 v[146:149], v3 offset:3072
	v_add_u32_e32 v3, s59, v224
	ds_read_b128 v[150:153], v3
	ds_read_b128 v[154:157], v3 offset:1024
	ds_read_b128 v[158:161], v3 offset:2048
	ds_read_b128 v[162:165], v3 offset:3072
	s_add_u32 s28, s28, 0x40000
	s_addc_u32 s29, s29, 0
	s_mov_b32 m0, s35
	ds_read_b128 v[166:169], v226 offset:32768
	ds_read_b128 v[170:173], v226 offset:33792
	ds_read_b128 v[174:177], v226 offset:34816
	ds_read_b128 v[178:181], v226 offset:35840
	ds_read_b128 v[182:185], v226 offset:36864
	ds_read_b128 v[186:189], v226 offset:37888
	ds_read_b128 v[190:193], v226 offset:38912
	ds_read_b128 v[194:197], v226 offset:39936
	global_load_lds_dwordx4 v198, s[28:29]
	s_mov_b32 m0, s36
	s_nop 0
	global_load_lds_dwordx4 v202, s[28:29]
	s_waitcnt vmcnt(8)
	s_waitcnt lgkmcnt(0)
	s_barrier
	v_mfma_f32_16x16x32_bf16 v[130:133], v[134:137], v[166:169], v[130:133]
	v_mfma_f32_16x16x32_bf16 v[126:129], v[142:145], v[166:169], v[126:129]
	v_mfma_f32_16x16x32_bf16 v[114:117], v[134:137], v[174:177], v[114:117]
	v_mfma_f32_16x16x32_bf16 v[110:113], v[142:145], v[174:177], v[110:113]
	v_mfma_f32_16x16x32_bf16 v[98:101], v[134:137], v[182:185], v[98:101]
	v_mfma_f32_16x16x32_bf16 v[94:97], v[142:145], v[182:185], v[94:97]
	v_mfma_f32_16x16x32_bf16 v[82:85], v[134:137], v[190:193], v[82:85]
	v_mfma_f32_16x16x32_bf16 v[78:81], v[142:145], v[190:193], v[78:81]
	v_mfma_f32_16x16x32_bf16 v[130:133], v[138:141], v[170:173], v[130:133]
	v_mfma_f32_16x16x32_bf16 v[126:129], v[146:149], v[170:173], v[126:129]
	v_mfma_f32_16x16x32_bf16 v[114:117], v[138:141], v[178:181], v[114:117]
	v_mfma_f32_16x16x32_bf16 v[110:113], v[146:149], v[178:181], v[110:113]
	v_mfma_f32_16x16x32_bf16 v[98:101], v[138:141], v[186:189], v[98:101]
	v_mfma_f32_16x16x32_bf16 v[94:97], v[146:149], v[186:189], v[94:97]
	v_mfma_f32_16x16x32_bf16 v[82:85], v[138:141], v[194:197], v[82:85]
	v_mfma_f32_16x16x32_bf16 v[78:81], v[146:149], v[194:197], v[78:81]
	v_mfma_f32_16x16x32_bf16 v[122:125], v[150:153], v[166:169], v[122:125]
	v_mfma_f32_16x16x32_bf16 v[118:121], v[158:161], v[166:169], v[118:121]
	v_mfma_f32_16x16x32_bf16 v[106:109], v[150:153], v[174:177], v[106:109]
	v_mfma_f32_16x16x32_bf16 v[102:105], v[158:161], v[174:177], v[102:105]
	v_mfma_f32_16x16x32_bf16 v[90:93], v[150:153], v[182:185], v[90:93]
	v_mfma_f32_16x16x32_bf16 v[86:89], v[158:161], v[182:185], v[86:89]
	v_mfma_f32_16x16x32_bf16 v[74:77], v[150:153], v[190:193], v[74:77]
	v_mfma_f32_16x16x32_bf16 v[70:73], v[158:161], v[190:193], v[70:73]
	v_mfma_f32_16x16x32_bf16 v[122:125], v[154:157], v[170:173], v[122:125]
	v_mfma_f32_16x16x32_bf16 v[118:121], v[162:165], v[170:173], v[118:121]
	v_mfma_f32_16x16x32_bf16 v[106:109], v[154:157], v[178:181], v[106:109]
	v_mfma_f32_16x16x32_bf16 v[102:105], v[162:165], v[178:181], v[102:105]
	v_mfma_f32_16x16x32_bf16 v[90:93], v[154:157], v[186:189], v[90:93]
	v_mfma_f32_16x16x32_bf16 v[86:89], v[162:165], v[186:189], v[86:89]
	v_mfma_f32_16x16x32_bf16 v[74:77], v[154:157], v[194:197], v[74:77]
	v_mfma_f32_16x16x32_bf16 v[70:73], v[162:165], v[194:197], v[70:73]
	s_barrier
; #define PG8_STAGE(bufoff, gbase, voff) do { _Pragma("unroll") for (int _i = 0; _i < 2; ++_i) \
;         __builtin_amdgcn_global_load_lds((const unsigned*)((const char*)(gbase) + (voff)[_i]), (PG8_LAS unsigned*)(lds + (bufoff) + ldsw + _i * 8192), 16, 0, 0); } while (0)
; #define PG8_LDA(dst, b, h) do { _Pragma("unroll") for (int m = 0; m < 4; ++m) _Pragma("unroll") for (int k = 0; k < 2; ++k) dst[m][k] = *(const PG8_LAS bf16x8*)(lds + PG8_SA(b, h) + aoff + m * 2048 + k * 1024); } while (0)
; #define PG8_MMA(ai, bj, At, Bt) do { __builtin_amdgcn_s_setprio(1); _Pragma("unroll") for (int m = 0; m < 4; ++m) _Pragma("unroll") for (int n = 0; n < 2; ++n) _Pragma("unroll") for (int k = 0; k < 2; ++k) \
;         acc[ai][bj][m][n] = __builtin_amdgcn_mfma_f32_16x16x32_bf16(Bt[n][k], At[m][k], acc[ai][bj][m][n], 0, 0, 0); __builtin_amdgcn_s_setprio(0); } while (0)
; #define PG8_WAIT_V(n) asm volatile("s_waitcnt vmcnt(" #n ")" ::: "memory")
; #define PG8_WAIT_L(n) asm volatile("s_waitcnt lgkmcnt(" #n ")" ::: "memory")
; #define PG8_BAR __builtin_amdgcn_s_barrier()
; #define PG8_SCHED __builtin_amdgcn_sched_barrier(0)
; template <class Epi, class Sched, bool ALIGN_EPI = false, bool SP2 = false>
; __device__ __forceinline__ void gemm_phase(PG8_LAS unsigned char* lds, const Gemm g, const Sched& S, const Epi& E) {
;     ...
;             PG8_LDA(At, 1, 1); PG8_STAGE(PG8_SB(1, 0), b3, voffB); PG8_STAGE(PG8_SB(1, 1), b3 + hstepB, voffB); PG8_STAGE(PG8_SA(1, 0), a3, voffA);
;             PG8_WAIT_V(8); PG8_WAIT_L(0); PG8_BAR; PG8_MMA(1, 0, At, B0); PG8_MMA(1, 1, At, B1); PG8_BAR; PG8_SCHED;
	s_add_i32 s28, s58, s31
	v_lshl_add_u64 v[8:9], v[218:219], 0, s[10:11]
	s_mov_b32 m0, s28
	ds_read_b128 v[166:169], v226 offset:49152
	ds_read_b128 v[170:173], v226 offset:50176
	ds_read_b128 v[174:177], v226 offset:51200
	ds_read_b128 v[178:181], v226 offset:52224
	ds_read_b128 v[182:185], v226 offset:53248
	ds_read_b128 v[186:189], v226 offset:54272
	ds_read_b128 v[190:193], v226 offset:55296
	ds_read_b128 v[194:197], v226 offset:56320
	global_load_lds_dwordx4 v[8:9], off
	s_add_i32 m0, s28, 0x2000
	s_add_u32 s26, s26, 0x10080
	v_lshl_add_u64 v[8:9], v[220:221], 0, s[10:11]
	s_addc_u32 s27, s27, 0
	s_add_i32 s28, s59, s31
	global_load_lds_dwordx4 v[8:9], off
	s_mov_b32 m0, s28
	s_nop 0
	global_load_lds_dwordx4 v200, s[26:27]
	s_add_i32 m0, s28, 0x2000
	s_nop 0
	global_load_lds_dwordx4 v204, s[26:27]
	v_lshl_add_u64 v[8:9], v[228:229], 0, s[10:11]
	s_mov_b32 m0, s39
	s_nop 0
	global_load_lds_dwordx4 v[8:9], off
	v_lshl_add_u64 v[8:9], v[230:231], 0, s[10:11]
	s_mov_b32 m0, s42
	s_nop 0
	global_load_lds_dwordx4 v[8:9], off
	s_waitcnt vmcnt(8)
	s_waitcnt lgkmcnt(0)
	s_barrier
	v_mfma_f32_16x16x32_bf16 v[66:69], v[134:137], v[166:169], v[66:69]
	v_mfma_f32_16x16x32_bf16 v[62:65], v[142:145], v[166:169], v[62:65]
	v_mfma_f32_16x16x32_bf16 v[50:53], v[134:137], v[174:177], v[50:53]
	v_mfma_f32_16x16x32_bf16 v[46:49], v[142:145], v[174:177], v[46:49]
	v_mfma_f32_16x16x32_bf16 v[34:37], v[134:137], v[182:185], v[34:37]
	v_mfma_f32_16x16x32_bf16 v[30:33], v[142:145], v[182:185], v[30:33]
	v_mfma_f32_16x16x32_bf16 v[18:21], v[134:137], v[190:193], v[18:21]
	v_mfma_f32_16x16x32_bf16 v[14:17], v[142:145], v[190:193], v[14:17]
	v_mfma_f32_16x16x32_bf16 v[66:69], v[138:141], v[170:173], v[66:69]
	v_mfma_f32_16x16x32_bf16 v[62:65], v[146:149], v[170:173], v[62:65]
	v_mfma_f32_16x16x32_bf16 v[50:53], v[138:141], v[178:181], v[50:53]
	v_mfma_f32_16x16x32_bf16 v[46:49], v[146:149], v[178:181], v[46:49]
	v_mfma_f32_16x16x32_bf16 v[34:37], v[138:141], v[186:189], v[34:37]
	v_mfma_f32_16x16x32_bf16 v[30:33], v[146:149], v[186:189], v[30:33]
	v_mfma_f32_16x16x32_bf16 v[18:21], v[138:141], v[194:197], v[18:21]
	v_mfma_f32_16x16x32_bf16 v[14:17], v[146:149], v[194:197], v[14:17]
	v_mfma_f32_16x16x32_bf16 v[58:61], v[150:153], v[166:169], v[58:61]
	v_mfma_f32_16x16x32_bf16 v[54:57], v[158:161], v[166:169], v[54:57]
	v_mfma_f32_16x16x32_bf16 v[42:45], v[150:153], v[174:177], v[42:45]
	v_mfma_f32_16x16x32_bf16 v[38:41], v[158:161], v[174:177], v[38:41]
	v_mfma_f32_16x16x32_bf16 v[26:29], v[150:153], v[182:185], v[26:29]
	v_mfma_f32_16x16x32_bf16 v[22:25], v[158:161], v[182:185], v[22:25]
	v_mfma_f32_16x16x32_bf16 v[8:11], v[150:153], v[190:193], v[10:13]
	v_mfma_f32_16x16x32_bf16 v[4:7], v[158:161], v[190:193], v[4:7]
	v_mfma_f32_16x16x32_bf16 v[58:61], v[154:157], v[170:173], v[58:61]
	v_mfma_f32_16x16x32_bf16 v[54:57], v[162:165], v[170:173], v[54:57]
	v_mfma_f32_16x16x32_bf16 v[42:45], v[154:157], v[178:181], v[42:45]
	v_mfma_f32_16x16x32_bf16 v[38:41], v[162:165], v[178:181], v[38:41]
	v_mfma_f32_16x16x32_bf16 v[26:29], v[154:157], v[186:189], v[26:29]
	v_mfma_f32_16x16x32_bf16 v[22:25], v[162:165], v[186:189], v[22:25]
	v_mfma_f32_16x16x32_bf16 v[10:13], v[154:157], v[194:197], v[8:11]
	v_mfma_f32_16x16x32_bf16 v[6:9], v[162:165], v[194:197], v[4:7]
	s_barrier
	s_add_i32 s64, s64, 2
	s_add_u32 s24, s24, 0x100
	s_addc_u32 s25, s25, 0
	s_cmp_gt_u32 s64, 13
	s_cbranch_scc1 .LBB0_1097

; #define PG8_STAGE(bufoff, gbase, voff) do { _Pragma("unroll") for (int _i = 0; _i < 2; ++_i) \
;         __builtin_amdgcn_global_load_lds((const unsigned*)((const char*)(gbase) + (voff)[_i]), (PG8_LAS unsigned*)(lds + (bufoff) + ldsw + _i * 8192), 16, 0, 0); } while (0)
; #define PG8_LDA(dst, b, h) do { _Pragma("unroll") for (int m = 0; m < 4; ++m) _Pragma("unroll") for (int k = 0; k < 2; ++k) dst[m][k] = *(const PG8_LAS bf16x8*)(lds + PG8_SA(b, h) + aoff + m * 2048 + k * 1024); } while (0)
; #define PG8_LDB(dst, b, h) do { _Pragma("unroll") for (int n = 0; n < 2; ++n) _Pragma("unroll") for (int k = 0; k < 2; ++k) dst[n][k] = *(const PG8_LAS bf16x8*)(lds + PG8_SB(b, h) + boff + n * 2048 + k * 1024); } while (0)
; #define PG8_MMA(ai, bj, At, Bt) do { __builtin_amdgcn_s_setprio(1); _Pragma("unroll") for (int m = 0; m < 4; ++m) _Pragma("unroll") for (int n = 0; n < 2; ++n) _Pragma("unroll") for (int k = 0; k < 2; ++k) \
;         acc[ai][bj][m][n] = __builtin_amdgcn_mfma_f32_16x16x32_bf16(Bt[n][k], At[m][k], acc[ai][bj][m][n], 0, 0, 0); __builtin_amdgcn_s_setprio(0); } while (0)
; #define PG8_WAIT_V(n) asm volatile("s_waitcnt vmcnt(" #n ")" ::: "memory")
; #define PG8_WAIT_L(n) asm volatile("s_waitcnt lgkmcnt(" #n ")" ::: "memory")
; #define PG8_BAR __builtin_amdgcn_s_barrier()
; #define PG8_SCHED __builtin_amdgcn_sched_barrier(0)
; template <class Epi, class Sched, bool ALIGN_EPI = false, bool SP2 = false>
; __device__ __forceinline__ void gemm_phase(PG8_LAS unsigned char* lds, const Gemm g, const Sched& S, const Epi& E) {
;     ...
;             const bool last = (t == nt - 2);
;             const char* a1 = cA + (size_t)(t + 1) * kstep;
;             const char* a2 = last ? nA : cA + (size_t)(t + 2) * kstep; const char* b2 = last ? nB : cB + (size_t)(t + 2) * kstep;
;             const char* a3 = a2 + kstep; const char* b3 = b2 + kstep;
;             if (last && has_next) S.a_ready(nxt);
;             if constexpr (SP2) {
;             PG8_LDB(B0, 0, 0); PG8_LDB(B1, 0, 1); PG8_SCHED; PG8_LDA(At, 0, 0); PG8_STAGE(PG8_SA(1, 1), a1 + hstep, voffA);
;             PG8_WAIT_V(8); PG8_WAIT_L(0); PG8_BAR; PG8_MMA(0, 0, At, B0); PG8_MMA(0, 1, At, B1); PG8_BAR; PG8_SCHED;
;             PG8_LDA(At, 0, 1); PG8_STAGE(PG8_SB(0, 0), b2, voffB); PG8_STAGE(PG8_SB(0, 1), b2 + hstepB, voffB); PG8_STAGE(PG8_SA(0, 0), a2, voffA);
.LBB0_1180:
	v_add_u32_e32 v144, s55, v142
	ds_read_b128 v[154:157], v144
	ds_read_b128 v[158:161], v144 offset:1024
	ds_read_b128 v[162:165], v144 offset:2048
	ds_read_b128 v[166:169], v144 offset:3072
	v_add_u32_e32 v144, s56, v142
	s_add_u32 s34, s10, s28
	ds_read_b128 v[170:173], v144
	ds_read_b128 v[174:177], v144 offset:1024
	ds_read_b128 v[178:181], v144 offset:2048
	ds_read_b128 v[182:185], v144 offset:3072
	s_addc_u32 s35, s11, s29
	s_add_u32 s34, s34, 0x100
	s_addc_u32 s35, s35, 0
	s_add_u32 s61, s25, s28
	s_addc_u32 s62, s57, s29
	s_cmpk_eq_i32 s28, 0x700
	s_cselect_b32 s37, s21, s35
	s_cselect_b32 s36, s58, s34
	s_cselect_b32 s35, s19, s62
	s_cselect_b32 s34, s59, s61
	v_lshl_add_u64 v[144:145], v[138:139], 0, s[28:29]
	s_add_i32 m0, s39, 0xc000
	ds_read_b128 v[186:189], v143
	ds_read_b128 v[190:193], v143 offset:1024
	ds_read_b128 v[194:197], v143 offset:2048
	ds_read_b128 v[198:201], v143 offset:3072
	ds_read_b128 v[202:205], v143 offset:4096
	ds_read_b128 v[206:209], v143 offset:5120
	ds_read_b128 v[216:219], v143 offset:6144
	ds_read_b128 v[224:227], v143 offset:7168
	global_load_lds_dwordx4 v[144:145], off
	v_lshl_add_u64 v[144:145], v[140:141], 0, s[28:29]
	s_add_i32 m0, s39, 0xe000
	s_nop 0
	global_load_lds_dwordx4 v[144:145], off
	s_waitcnt vmcnt(8)
	s_waitcnt lgkmcnt(0)
	s_barrier
	v_mfma_f32_16x16x32_bf16 v[150:153], v[154:157], v[186:189], v[150:153]
	v_mfma_f32_16x16x32_bf16 v[144:147], v[162:165], v[186:189], v[146:149]
	v_mfma_f32_16x16x32_bf16 v[110:113], v[154:157], v[194:197], v[110:113]
	v_mfma_f32_16x16x32_bf16 v[106:109], v[162:165], v[194:197], v[106:109]
	v_mfma_f32_16x16x32_bf16 v[94:97], v[154:157], v[202:205], v[94:97]
	v_mfma_f32_16x16x32_bf16 v[90:93], v[162:165], v[202:205], v[90:93]
	v_mfma_f32_16x16x32_bf16 v[78:81], v[154:157], v[216:219], v[78:81]
	v_mfma_f32_16x16x32_bf16 v[74:77], v[162:165], v[216:219], v[74:77]
	v_mfma_f32_16x16x32_bf16 v[150:153], v[158:161], v[190:193], v[150:153]
	v_mfma_f32_16x16x32_bf16 v[144:147], v[166:169], v[190:193], v[144:147]
	v_mfma_f32_16x16x32_bf16 v[110:113], v[158:161], v[198:201], v[110:113]
	v_mfma_f32_16x16x32_bf16 v[106:109], v[166:169], v[198:201], v[106:109]
	v_mfma_f32_16x16x32_bf16 v[94:97], v[158:161], v[206:209], v[94:97]
	v_mfma_f32_16x16x32_bf16 v[90:93], v[166:169], v[206:209], v[90:93]
	v_mfma_f32_16x16x32_bf16 v[78:81], v[158:161], v[224:227], v[78:81]
	v_mfma_f32_16x16x32_bf16 v[74:77], v[166:169], v[224:227], v[74:77]
	v_mfma_f32_16x16x32_bf16 v[118:121], v[170:173], v[186:189], v[118:121]
	v_mfma_f32_16x16x32_bf16 v[114:117], v[178:181], v[186:189], v[114:117]
	v_mfma_f32_16x16x32_bf16 v[102:105], v[170:173], v[194:197], v[102:105]
	v_mfma_f32_16x16x32_bf16 v[98:101], v[178:181], v[194:197], v[98:101]
	v_mfma_f32_16x16x32_bf16 v[86:89], v[170:173], v[202:205], v[86:89]
	v_mfma_f32_16x16x32_bf16 v[82:85], v[178:181], v[202:205], v[82:85]
	v_mfma_f32_16x16x32_bf16 v[70:73], v[170:173], v[216:219], v[70:73]
	v_mfma_f32_16x16x32_bf16 v[66:69], v[178:181], v[216:219], v[66:69]
	v_mfma_f32_16x16x32_bf16 v[118:121], v[174:177], v[190:193], v[118:121]
	v_mfma_f32_16x16x32_bf16 v[114:117], v[182:185], v[190:193], v[114:117]
	v_mfma_f32_16x16x32_bf16 v[102:105], v[174:177], v[198:201], v[102:105]
	v_mfma_f32_16x16x32_bf16 v[98:101], v[182:185], v[198:201], v[98:101]
	v_mfma_f32_16x16x32_bf16 v[86:89], v[174:177], v[206:209], v[86:89]
	v_mfma_f32_16x16x32_bf16 v[82:85], v[182:185], v[206:209], v[82:85]
	v_mfma_f32_16x16x32_bf16 v[70:73], v[174:177], v[224:227], v[70:73]
	v_mfma_f32_16x16x32_bf16 v[66:69], v[182:185], v[224:227], v[66:69]
	s_barrier
	s_add_i32 s61, s55, s38
	v_lshl_add_u64 v[210:211], s[34:35], 0, v[124:125]
	s_mov_b32 m0, s61
	ds_read_b128 v[186:189], v143 offset:16384
	ds_read_b128 v[190:193], v143 offset:17408
	ds_read_b128 v[194:197], v143 offset:18432
	ds_read_b128 v[198:201], v143 offset:19456
	ds_read_b128 v[202:205], v143 offset:20480
	ds_read_b128 v[206:209], v143 offset:21504
	ds_read_b128 v[216:219], v143 offset:22528
	ds_read_b128 v[224:227], v143 offset:23552
	global_load_lds_dwordx4 v124, s[34:35]
	s_add_i32 m0, s61, 0x2000
	s_add_u32 s62, s34, 0x10000
	v_lshl_add_u64 v[220:221], s[34:35], 0, v[128:129]
	s_addc_u32 s63, s35, 0
	s_add_i32 s61, s56, s38
	global_load_lds_dwordx4 v128, s[34:35]
	s_mov_b32 m0, s61
	v_lshl_add_u64 v[228:229], s[36:37], 0, v[122:123]
	global_load_lds_dwordx4 v124, s[62:63]
	v_lshl_add_u64 v[148:149], s[62:63], 0, v[128:129]
	s_add_i32 m0, s61, 0x2000
	v_lshl_add_u64 v[230:231], s[36:37], 0, v[126:127]
	global_load_lds_dwordx4 v128, s[62:63]
	s_mov_b32 m0, s39
	s_nop 0
	global_load_lds_dwordx4 v122, s[36:37]
	s_mov_b32 m0, s42
	s_nop 0
	global_load_lds_dwordx4 v126, s[36:37]
	s_waitcnt vmcnt(8)
	s_waitcnt lgkmcnt(0)
	s_barrier
; #define PG8_STAGE(bufoff, gbase, voff) do { _Pragma("unroll") for (int _i = 0; _i < 2; ++_i) \
;         __builtin_amdgcn_global_load_lds((const unsigned*)((const char*)(gbase) + (voff)[_i]), (PG8_LAS unsigned*)(lds + (bufoff) + ldsw + _i * 8192), 16, 0, 0); } while (0)
; #define PG8_LDA(dst, b, h) do { _Pragma("unroll") for (int m = 0; m < 4; ++m) _Pragma("unroll") for (int k = 0; k < 2; ++k) dst[m][k] = *(const PG8_LAS bf16x8*)(lds + PG8_SA(b, h) + aoff + m * 2048 + k * 1024); } while (0)
; #define PG8_LDB(dst, b, h) do { _Pragma("unroll") for (int n = 0; n < 2; ++n) _Pragma("unroll") for (int k = 0; k < 2; ++k) dst[n][k] = *(const PG8_LAS bf16x8*)(lds + PG8_SB(b, h) + boff + n * 2048 + k * 1024); } while (0)
; #define PG8_MMA(ai, bj, At, Bt) do { __builtin_amdgcn_s_setprio(1); _Pragma("unroll") for (int m = 0; m < 4; ++m) _Pragma("unroll") for (int n = 0; n < 2; ++n) _Pragma("unroll") for (int k = 0; k < 2; ++k) \
;         acc[ai][bj][m][n] = __builtin_amdgcn_mfma_f32_16x16x32_bf16(Bt[n][k], At[m][k], acc[ai][bj][m][n], 0, 0, 0); __builtin_amdgcn_s_setprio(0); } while (0)
; #define PG8_WAIT_V(n) asm volatile("s_waitcnt vmcnt(" #n ")" ::: "memory")
; #define PG8_WAIT_L(n) asm volatile("s_waitcnt lgkmcnt(" #n ")" ::: "memory")
; #define PG8_BAR __builtin_amdgcn_s_barrier()
; #define PG8_SCHED __builtin_amdgcn_sched_barrier(0)
; template <class Epi, class Sched, bool ALIGN_EPI = false, bool SP2 = false>
; __device__ __forceinline__ void gemm_phase(PG8_LAS unsigned char* lds, const Gemm g, const Sched& S, const Epi& E) {
;     ...
;             PG8_WAIT_V(8); PG8_WAIT_L(0); PG8_BAR; PG8_MMA(1, 0, At, B0); PG8_MMA(1, 1, At, B1); PG8_BAR; PG8_SCHED;
;             PG8_LDB(B0, 1, 0); PG8_LDB(B1, 1, 1); PG8_SCHED; PG8_LDA(At, 1, 0); PG8_STAGE(PG8_SA(0, 1), a2 + hstep, voffA);
;             PG8_WAIT_V(8); PG8_WAIT_L(0); PG8_BAR; PG8_MMA(0, 0, At, B0); PG8_MMA(0, 1, At, B1); PG8_BAR; PG8_SCHED;
	v_mfma_f32_16x16x32_bf16 v[62:65], v[154:157], v[186:189], v[62:65]
	v_mfma_f32_16x16x32_bf16 v[58:61], v[162:165], v[186:189], v[58:61]
	v_mfma_f32_16x16x32_bf16 v[46:49], v[154:157], v[194:197], v[46:49]
	v_mfma_f32_16x16x32_bf16 v[42:45], v[162:165], v[194:197], v[42:45]
	v_mfma_f32_16x16x32_bf16 v[30:33], v[154:157], v[202:205], v[30:33]
	v_mfma_f32_16x16x32_bf16 v[26:29], v[162:165], v[202:205], v[26:29]
	v_mfma_f32_16x16x32_bf16 v[14:17], v[154:157], v[216:219], v[14:17]
	v_mfma_f32_16x16x32_bf16 v[10:13], v[162:165], v[216:219], v[10:13]
	v_mfma_f32_16x16x32_bf16 v[62:65], v[158:161], v[190:193], v[62:65]
	v_mfma_f32_16x16x32_bf16 v[58:61], v[166:169], v[190:193], v[58:61]
	v_mfma_f32_16x16x32_bf16 v[46:49], v[158:161], v[198:201], v[46:49]
	v_mfma_f32_16x16x32_bf16 v[42:45], v[166:169], v[198:201], v[42:45]
	v_mfma_f32_16x16x32_bf16 v[30:33], v[158:161], v[206:209], v[30:33]
	v_mfma_f32_16x16x32_bf16 v[26:29], v[166:169], v[206:209], v[26:29]
	v_mfma_f32_16x16x32_bf16 v[14:17], v[158:161], v[224:227], v[14:17]
	v_mfma_f32_16x16x32_bf16 v[10:13], v[166:169], v[224:227], v[10:13]
	v_mfma_f32_16x16x32_bf16 v[54:57], v[170:173], v[186:189], v[54:57]
	v_mfma_f32_16x16x32_bf16 v[50:53], v[178:181], v[186:189], v[50:53]
	v_mfma_f32_16x16x32_bf16 v[38:41], v[170:173], v[194:197], v[38:41]
	v_mfma_f32_16x16x32_bf16 v[34:37], v[178:181], v[194:197], v[34:37]
	v_mfma_f32_16x16x32_bf16 v[22:25], v[170:173], v[202:205], v[22:25]
	v_mfma_f32_16x16x32_bf16 v[18:21], v[178:181], v[202:205], v[18:21]
	v_mfma_f32_16x16x32_bf16 v[6:9], v[170:173], v[216:219], v[6:9]
	v_mfma_f32_16x16x32_bf16 v[2:5], v[178:181], v[216:219], v[2:5]
	v_mfma_f32_16x16x32_bf16 v[54:57], v[174:177], v[190:193], v[54:57]
	v_mfma_f32_16x16x32_bf16 v[50:53], v[182:185], v[190:193], v[50:53]
	v_mfma_f32_16x16x32_bf16 v[38:41], v[174:177], v[198:201], v[38:41]
	v_mfma_f32_16x16x32_bf16 v[34:37], v[182:185], v[198:201], v[34:37]
	v_mfma_f32_16x16x32_bf16 v[22:25], v[174:177], v[206:209], v[22:25]
	v_mfma_f32_16x16x32_bf16 v[18:21], v[182:185], v[206:209], v[18:21]
	v_mfma_f32_16x16x32_bf16 v[6:9], v[174:177], v[224:227], v[6:9]
	v_mfma_f32_16x16x32_bf16 v[2:5], v[182:185], v[224:227], v[2:5]
	s_barrier
	s_add_i32 s61, 0, 0x18000
	v_add_u32_e32 v148, s61, v142
	s_add_i32 s62, 0, 0x1c000
	ds_read_b128 v[154:157], v148
	ds_read_b128 v[158:161], v148 offset:1024
	ds_read_b128 v[162:165], v148 offset:2048
	ds_read_b128 v[166:169], v148 offset:3072
	v_add_u32_e32 v148, s62, v142
	ds_read_b128 v[170:173], v148
	ds_read_b128 v[174:177], v148 offset:1024
	ds_read_b128 v[178:181], v148 offset:2048
	ds_read_b128 v[182:185], v148 offset:3072
	s_add_u32 s36, s36, 0x40000
	s_addc_u32 s37, s37, 0
	s_mov_b32 m0, s44
	ds_read_b128 v[186:189], v143 offset:32768
	ds_read_b128 v[190:193], v143 offset:33792
	ds_read_b128 v[194:197], v143 offset:34816
	ds_read_b128 v[198:201], v143 offset:35840
	ds_read_b128 v[202:205], v143 offset:36864
	ds_read_b128 v[206:209], v143 offset:37888
	ds_read_b128 v[216:219], v143 offset:38912
	ds_read_b128 v[224:227], v143 offset:39936
	global_load_lds_dwordx4 v122, s[36:37]
	s_mov_b32 m0, s45
	s_nop 0
	global_load_lds_dwordx4 v126, s[36:37]
	s_waitcnt vmcnt(8)
	s_waitcnt lgkmcnt(0)
	s_barrier
	v_mfma_f32_16x16x32_bf16 v[148:151], v[154:157], v[186:189], v[150:153]
	v_mfma_f32_16x16x32_bf16 v[144:147], v[162:165], v[186:189], v[144:147]
	v_mfma_f32_16x16x32_bf16 v[110:113], v[154:157], v[194:197], v[110:113]
	v_mfma_f32_16x16x32_bf16 v[106:109], v[162:165], v[194:197], v[106:109]
	v_mfma_f32_16x16x32_bf16 v[94:97], v[154:157], v[202:205], v[94:97]
	v_mfma_f32_16x16x32_bf16 v[90:93], v[162:165], v[202:205], v[90:93]
	v_mfma_f32_16x16x32_bf16 v[78:81], v[154:157], v[216:219], v[78:81]
	v_mfma_f32_16x16x32_bf16 v[74:77], v[162:165], v[216:219], v[74:77]
	v_mfma_f32_16x16x32_bf16 v[150:153], v[158:161], v[190:193], v[148:151]
	v_mfma_f32_16x16x32_bf16 v[146:149], v[166:169], v[190:193], v[144:147]
	v_mfma_f32_16x16x32_bf16 v[110:113], v[158:161], v[198:201], v[110:113]
	v_mfma_f32_16x16x32_bf16 v[106:109], v[166:169], v[198:201], v[106:109]
	v_mfma_f32_16x16x32_bf16 v[94:97], v[158:161], v[206:209], v[94:97]
	v_mfma_f32_16x16x32_bf16 v[90:93], v[166:169], v[206:209], v[90:93]
	v_mfma_f32_16x16x32_bf16 v[78:81], v[158:161], v[224:227], v[78:81]
	v_mfma_f32_16x16x32_bf16 v[74:77], v[166:169], v[224:227], v[74:77]
	v_mfma_f32_16x16x32_bf16 v[118:121], v[170:173], v[186:189], v[118:121]
	v_mfma_f32_16x16x32_bf16 v[114:117], v[178:181], v[186:189], v[114:117]
	v_mfma_f32_16x16x32_bf16 v[102:105], v[170:173], v[194:197], v[102:105]
	v_mfma_f32_16x16x32_bf16 v[98:101], v[178:181], v[194:197], v[98:101]
	v_mfma_f32_16x16x32_bf16 v[86:89], v[170:173], v[202:205], v[86:89]
	v_mfma_f32_16x16x32_bf16 v[82:85], v[178:181], v[202:205], v[82:85]
	v_mfma_f32_16x16x32_bf16 v[70:73], v[170:173], v[216:219], v[70:73]
	v_mfma_f32_16x16x32_bf16 v[66:69], v[178:181], v[216:219], v[66:69]
	v_mfma_f32_16x16x32_bf16 v[118:121], v[174:177], v[190:193], v[118:121]
	v_mfma_f32_16x16x32_bf16 v[114:117], v[182:185], v[190:193], v[114:117]
	v_mfma_f32_16x16x32_bf16 v[102:105], v[174:177], v[198:201], v[102:105]
	v_mfma_f32_16x16x32_bf16 v[98:101], v[182:185], v[198:201], v[98:101]
	v_mfma_f32_16x16x32_bf16 v[86:89], v[174:177], v[206:209], v[86:89]
	v_mfma_f32_16x16x32_bf16 v[82:85], v[182:185], v[206:209], v[82:85]
	v_mfma_f32_16x16x32_bf16 v[70:73], v[174:177], v[224:227], v[70:73]
	v_mfma_f32_16x16x32_bf16 v[66:69], v[182:185], v[224:227], v[66:69]
	s_barrier
; #define PG8_STAGE(bufoff, gbase, voff) do { _Pragma("unroll") for (int _i = 0; _i < 2; ++_i) \
;         __builtin_amdgcn_global_load_lds((const unsigned*)((const char*)(gbase) + (voff)[_i]), (PG8_LAS unsigned*)(lds + (bufoff) + ldsw + _i * 8192), 16, 0, 0); } while (0)
; #define PG8_LDA(dst, b, h) do { _Pragma("unroll") for (int m = 0; m < 4; ++m) _Pragma("unroll") for (int k = 0; k < 2; ++k) dst[m][k] = *(const PG8_LAS bf16x8*)(lds + PG8_SA(b, h) + aoff + m * 2048 + k * 1024); } while (0)
; #define PG8_MMA(ai, bj, At, Bt) do { __builtin_amdgcn_s_setprio(1); _Pragma("unroll") for (int m = 0; m < 4; ++m) _Pragma("unroll") for (int n = 0; n < 2; ++n) _Pragma("unroll") for (int k = 0; k < 2; ++k) \
;         acc[ai][bj][m][n] = __builtin_amdgcn_mfma_f32_16x16x32_bf16(Bt[n][k], At[m][k], acc[ai][bj][m][n], 0, 0, 0); __builtin_amdgcn_s_setprio(0); } while (0)
; #define PG8_WAIT_V(n) asm volatile("s_waitcnt vmcnt(" #n ")" ::: "memory")
; #define PG8_WAIT_L(n) asm volatile("s_waitcnt lgkmcnt(" #n ")" ::: "memory")
; #define PG8_BAR __builtin_amdgcn_s_barrier()
; #define PG8_SCHED __builtin_amdgcn_sched_barrier(0)
; template <class Epi, class Sched, bool ALIGN_EPI = false, bool SP2 = false>
; __device__ __forceinline__ void gemm_phase(PG8_LAS unsigned char* lds, const Gemm g, const Sched& S, const Epi& E) {
;     ...
;             PG8_LDA(At, 1, 1); PG8_STAGE(PG8_SB(1, 0), b3, voffB); PG8_STAGE(PG8_SB(1, 1), b3 + hstepB, voffB); PG8_STAGE(PG8_SA(1, 0), a3, voffA);
;             PG8_WAIT_V(8); PG8_WAIT_L(0); PG8_BAR; PG8_MMA(1, 0, At, B0); PG8_MMA(1, 1, At, B1); PG8_BAR; PG8_SCHED;
;     ...
;         if (!has_next) break;
; #pragma unroll
;         for (int a = 0; a < 2; ++a)
; #pragma unroll
;             for (int b = 0; b < 2; ++b)
; #pragma unroll
;                 for (int m = 0; m < 4; ++m)
; #pragma unroll
;                     for (int n = 0; n < 2; ++n) acc[a][b][m][n] = (f32x4){0.f, 0.f, 0.f, 0.f};
;         cur = nxt; cA = nA; cB = nB; ++ui;
	s_add_i32 s36, s61, s38
	v_lshl_add_u64 v[144:145], v[210:211], 0, s[16:17]
	s_mov_b32 m0, s36
	ds_read_b128 v[186:189], v143 offset:49152
	ds_read_b128 v[190:193], v143 offset:50176
	ds_read_b128 v[194:197], v143 offset:51200
	ds_read_b128 v[198:201], v143 offset:52224
	ds_read_b128 v[202:205], v143 offset:53248
	ds_read_b128 v[206:209], v143 offset:54272
	ds_read_b128 v[216:219], v143 offset:55296
	ds_read_b128 v[224:227], v143 offset:56320
	global_load_lds_dwordx4 v[144:145], off
	s_add_i32 m0, s36, 0x2000
	s_add_u32 s34, s34, 0x10080
	v_lshl_add_u64 v[144:145], v[220:221], 0, s[16:17]
	s_addc_u32 s35, s35, 0
	s_add_i32 s36, s62, s38
	global_load_lds_dwordx4 v[144:145], off
	s_mov_b32 m0, s36
	s_nop 0
	global_load_lds_dwordx4 v124, s[34:35]
	s_add_i32 m0, s36, 0x2000
	s_nop 0
	global_load_lds_dwordx4 v128, s[34:35]
	v_lshl_add_u64 v[144:145], v[228:229], 0, s[16:17]
	s_mov_b32 m0, s46
	s_nop 0
	global_load_lds_dwordx4 v[144:145], off
	v_lshl_add_u64 v[144:145], v[230:231], 0, s[16:17]
	s_mov_b32 m0, s47
	s_nop 0
	global_load_lds_dwordx4 v[144:145], off
	s_waitcnt vmcnt(8)
	s_waitcnt lgkmcnt(0)
	s_barrier
	v_mfma_f32_16x16x32_bf16 v[62:65], v[154:157], v[186:189], v[62:65]
	v_mfma_f32_16x16x32_bf16 v[58:61], v[162:165], v[186:189], v[58:61]
	v_mfma_f32_16x16x32_bf16 v[46:49], v[154:157], v[194:197], v[46:49]
	v_mfma_f32_16x16x32_bf16 v[42:45], v[162:165], v[194:197], v[42:45]
	v_mfma_f32_16x16x32_bf16 v[30:33], v[154:157], v[202:205], v[30:33]
	v_mfma_f32_16x16x32_bf16 v[26:29], v[162:165], v[202:205], v[26:29]
	v_mfma_f32_16x16x32_bf16 v[14:17], v[154:157], v[216:219], v[14:17]
	v_mfma_f32_16x16x32_bf16 v[10:13], v[162:165], v[216:219], v[10:13]
	v_mfma_f32_16x16x32_bf16 v[62:65], v[158:161], v[190:193], v[62:65]
	v_mfma_f32_16x16x32_bf16 v[58:61], v[166:169], v[190:193], v[58:61]
	v_mfma_f32_16x16x32_bf16 v[46:49], v[158:161], v[198:201], v[46:49]
	v_mfma_f32_16x16x32_bf16 v[42:45], v[166:169], v[198:201], v[42:45]
	v_mfma_f32_16x16x32_bf16 v[30:33], v[158:161], v[206:209], v[30:33]
	v_mfma_f32_16x16x32_bf16 v[26:29], v[166:169], v[206:209], v[26:29]
	v_mfma_f32_16x16x32_bf16 v[14:17], v[158:161], v[224:227], v[14:17]
	v_mfma_f32_16x16x32_bf16 v[10:13], v[166:169], v[224:227], v[10:13]
	v_mfma_f32_16x16x32_bf16 v[54:57], v[170:173], v[186:189], v[54:57]
	v_mfma_f32_16x16x32_bf16 v[50:53], v[178:181], v[186:189], v[50:53]
	v_mfma_f32_16x16x32_bf16 v[38:41], v[170:173], v[194:197], v[38:41]
	v_mfma_f32_16x16x32_bf16 v[34:37], v[178:181], v[194:197], v[34:37]
	v_mfma_f32_16x16x32_bf16 v[22:25], v[170:173], v[202:205], v[22:25]
	v_mfma_f32_16x16x32_bf16 v[18:21], v[178:181], v[202:205], v[18:21]
	v_mfma_f32_16x16x32_bf16 v[6:9], v[170:173], v[216:219], v[6:9]
	v_mfma_f32_16x16x32_bf16 v[2:5], v[178:181], v[216:219], v[2:5]
	v_mfma_f32_16x16x32_bf16 v[54:57], v[174:177], v[190:193], v[54:57]
	v_mfma_f32_16x16x32_bf16 v[50:53], v[182:185], v[190:193], v[50:53]
	v_mfma_f32_16x16x32_bf16 v[38:41], v[174:177], v[198:201], v[38:41]
	v_mfma_f32_16x16x32_bf16 v[34:37], v[182:185], v[198:201], v[34:37]
	v_mfma_f32_16x16x32_bf16 v[22:25], v[174:177], v[206:209], v[22:25]
	v_mfma_f32_16x16x32_bf16 v[18:21], v[182:185], v[206:209], v[18:21]
	v_mfma_f32_16x16x32_bf16 v[6:9], v[174:177], v[224:227], v[6:9]
	v_mfma_f32_16x16x32_bf16 v[2:5], v[182:185], v[224:227], v[2:5]
	s_barrier
	s_add_i32 s60, s60, 2
	s_add_u32 s28, s28, 0x100
	s_addc_u32 s29, s29, 0
	s_cmp_gt_u32 s60, 13
	s_cbranch_scc0 .LBB0_1180
	s_add_u32 s28, s25, 0xffffff00
	s_addc_u32 s29, s57, -1
	s_andn2_b64 vcc, exec, s[8:9]
	s_cbranch_vccnz .LBB0_1171
	v_mov_b32_e32 v2, 0
	s_mov_b32 s0, s18
	s_mov_b32 s14, s20
	s_mov_b64 s[10:11], s[26:27]
	s_mov_b32 s54, s24
	v_mov_b32_e32 v3, 0
	v_mov_b64_e32 v[4:5], 0
	v_mov_b64_e32 v[6:7], 0
	v_mov_b64_e32 v[8:9], 0
	v_mov_b64_e32 v[18:19], 0
	v_mov_b64_e32 v[20:21], 0
	v_mov_b64_e32 v[22:23], 0
	v_mov_b64_e32 v[24:25], 0
	v_mov_b64_e32 v[34:35], 0
	v_mov_b64_e32 v[36:37], 0
	v_mov_b64_e32 v[38:39], 0
	v_mov_b64_e32 v[40:41], 0
	v_mov_b64_e32 v[50:51], 0
	v_mov_b64_e32 v[52:53], 0
	v_mov_b64_e32 v[54:55], 0
	v_mov_b64_e32 v[56:57], 0
	v_mov_b64_e32 v[10:11], 0
	v_mov_b64_e32 v[12:13], 0
	v_mov_b64_e32 v[14:15], 0
	v_mov_b64_e32 v[16:17], 0
	v_mov_b64_e32 v[26:27], 0
	v_mov_b64_e32 v[28:29], 0
	v_mov_b64_e32 v[30:31], 0
	v_mov_b64_e32 v[32:33], 0
	v_mov_b64_e32 v[42:43], 0
	v_mov_b64_e32 v[44:45], 0
	v_mov_b64_e32 v[46:47], 0
	v_mov_b64_e32 v[48:49], 0
	v_mov_b64_e32 v[58:59], 0
	v_mov_b64_e32 v[60:61], 0
	v_mov_b64_e32 v[62:63], 0
	v_mov_b64_e32 v[64:65], 0
	v_mov_b64_e32 v[66:67], 0
	v_mov_b64_e32 v[68:69], 0
	v_mov_b64_e32 v[70:71], 0
	v_mov_b64_e32 v[72:73], 0
	v_mov_b64_e32 v[82:83], 0
	v_mov_b64_e32 v[84:85], 0
	v_mov_b64_e32 v[86:87], 0
	v_mov_b64_e32 v[88:89], 0
	v_mov_b64_e32 v[98:99], 0
	v_mov_b64_e32 v[100:101], 0
	v_mov_b64_e32 v[102:103], 0
	v_mov_b64_e32 v[104:105], 0
	v_mov_b64_e32 v[114:115], 0
	v_mov_b64_e32 v[116:117], 0
	v_mov_b64_e32 v[118:119], 0
	v_mov_b64_e32 v[120:121], 0
	v_mov_b64_e32 v[74:75], 0
	v_mov_b64_e32 v[76:77], 0
	v_mov_b64_e32 v[78:79], 0
	v_mov_b64_e32 v[80:81], 0
	v_mov_b64_e32 v[90:91], 0
	v_mov_b64_e32 v[92:93], 0
	v_mov_b64_e32 v[94:95], 0
	v_mov_b64_e32 v[96:97], 0
	v_mov_b64_e32 v[106:107], 0
	v_mov_b64_e32 v[108:109], 0
	v_mov_b64_e32 v[110:111], 0
	v_mov_b64_e32 v[112:113], 0
	v_mov_b64_e32 v[146:147], 0
	v_mov_b64_e32 v[148:149], 0
	v_mov_b64_e32 v[150:151], 0
	v_mov_b64_e32 v[152:153], 0
	s_andn2_b64 vcc, exec, s[6:7]
	s_cbranch_vccnz .LBB0_1172

; #define PG8_STAGE(bufoff, gbase, voff) do { _Pragma("unroll") for (int _i = 0; _i < 2; ++_i) \
;         __builtin_amdgcn_global_load_lds((const unsigned*)((const char*)(gbase) + (voff)[_i]), (PG8_LAS unsigned*)(lds + (bufoff) + ldsw + _i * 8192), 16, 0, 0); } while (0)
; #define PG8_LDA(dst, b, h) do { _Pragma("unroll") for (int m = 0; m < 4; ++m) _Pragma("unroll") for (int k = 0; k < 2; ++k) dst[m][k] = *(const PG8_LAS bf16x8*)(lds + PG8_SA(b, h) + aoff + m * 2048 + k * 1024); } while (0)
; #define PG8_LDB(dst, b, h) do { _Pragma("unroll") for (int n = 0; n < 2; ++n) _Pragma("unroll") for (int k = 0; k < 2; ++k) dst[n][k] = *(const PG8_LAS bf16x8*)(lds + PG8_SB(b, h) + boff + n * 2048 + k * 1024); } while (0)
; #define PG8_MMA(ai, bj, At, Bt) do { __builtin_amdgcn_s_setprio(1); _Pragma("unroll") for (int m = 0; m < 4; ++m) _Pragma("unroll") for (int n = 0; n < 2; ++n) _Pragma("unroll") for (int k = 0; k < 2; ++k) \
;         acc[ai][bj][m][n] = __builtin_amdgcn_mfma_f32_16x16x32_bf16(Bt[n][k], At[m][k], acc[ai][bj][m][n], 0, 0, 0); __builtin_amdgcn_s_setprio(0); } while (0)
; #define PG8_WAIT_V(n) asm volatile("s_waitcnt vmcnt(" #n ")" ::: "memory")
; #define PG8_WAIT_L(n) asm volatile("s_waitcnt lgkmcnt(" #n ")" ::: "memory")
; #define PG8_BAR __builtin_amdgcn_s_barrier()
; #define PG8_SCHED __builtin_amdgcn_sched_barrier(0)
; template <class Epi, class Sched, bool ALIGN_EPI = false, bool SP2 = false>
; __device__ __forceinline__ void gemm_phase(PG8_LAS unsigned char* lds, const Gemm g, const Sched& S, const Epi& E) {
;     ...
;             const bool last = (t == nt - 2);
;             const char* a1 = cA + (size_t)(t + 1) * kstep;
;             const char* a2 = last ? nA : cA + (size_t)(t + 2) * kstep; const char* b2 = last ? nB : cB + (size_t)(t + 2) * kstep;
;             const char* a3 = a2 + kstep; const char* b3 = b2 + kstep;
;             if (last && has_next) S.a_ready(nxt);
;             if constexpr (SP2) {
;             PG8_LDB(B0, 0, 0); PG8_LDB(B1, 0, 1); PG8_SCHED; PG8_LDA(At, 0, 0); PG8_STAGE(PG8_SA(1, 1), a1 + hstep, voffA);
;             PG8_WAIT_V(8); PG8_WAIT_L(0); PG8_BAR; PG8_MMA(0, 0, At, B0); PG8_MMA(0, 1, At, B1); PG8_BAR; PG8_SCHED;
;             PG8_LDA(At, 0, 1); PG8_STAGE(PG8_SB(0, 0), b2, voffB); PG8_STAGE(PG8_SB(0, 1), b2 + hstepB, voffB); PG8_STAGE(PG8_SA(0, 0), a2, voffA);
.LBB0_1313:
	ds_read_b128 v[146:149], v154
	ds_read_b128 v[158:161], v154 offset:1024
	ds_read_b128 v[162:165], v154 offset:2048
	ds_read_b128 v[166:169], v154 offset:3072
	ds_read_b128 v[170:173], v155
	ds_read_b128 v[174:177], v155 offset:1024
	ds_read_b128 v[178:181], v155 offset:2048
	ds_read_b128 v[182:185], v155 offset:3072
	s_add_u32 s40, s38, 0xfffc0080
	s_addc_u32 s41, s39, -1
	s_cmp_eq_u32 s61, 12
	s_cselect_b32 s43, s9, s41
	s_cselect_b32 s42, s27, s40
	s_cselect_b32 s41, s25, s60
	s_cselect_b32 s40, s37, s59
	v_lshl_add_u64 v[150:151], s[38:39], 0, v[138:139]
	s_add_i32 m0, s31, 0xc000
	ds_read_b128 v[186:189], v156
	ds_read_b128 v[190:193], v156 offset:1024
	ds_read_b128 v[194:197], v156 offset:2048
	ds_read_b128 v[198:201], v156 offset:3072
	ds_read_b128 v[202:205], v156 offset:4096
	ds_read_b128 v[206:209], v156 offset:5120
	ds_read_b128 v[210:213], v156 offset:6144
	ds_read_b128 v[214:217], v156 offset:7168
	global_load_lds_dwordx4 v[150:151], off
	v_lshl_add_u64 v[150:151], s[38:39], 0, v[140:141]
	s_add_i32 m0, s31, 0xe000
	s_nop 0
	global_load_lds_dwordx4 v[150:151], off
	s_waitcnt vmcnt(8)
	s_waitcnt lgkmcnt(0)
	s_barrier
	v_mfma_f32_16x16x32_bf16 v[126:129], v[146:149], v[186:189], v[126:129]
	v_mfma_f32_16x16x32_bf16 v[122:125], v[162:165], v[186:189], v[122:125]
	v_mfma_f32_16x16x32_bf16 v[110:113], v[146:149], v[194:197], v[110:113]
	v_mfma_f32_16x16x32_bf16 v[106:109], v[162:165], v[194:197], v[106:109]
	v_mfma_f32_16x16x32_bf16 v[94:97], v[146:149], v[202:205], v[94:97]
	v_mfma_f32_16x16x32_bf16 v[90:93], v[162:165], v[202:205], v[90:93]
	v_mfma_f32_16x16x32_bf16 v[78:81], v[146:149], v[210:213], v[78:81]
	v_mfma_f32_16x16x32_bf16 v[74:77], v[162:165], v[210:213], v[74:77]
	v_mfma_f32_16x16x32_bf16 v[126:129], v[158:161], v[190:193], v[126:129]
	v_mfma_f32_16x16x32_bf16 v[122:125], v[166:169], v[190:193], v[122:125]
	v_mfma_f32_16x16x32_bf16 v[110:113], v[158:161], v[198:201], v[110:113]
	v_mfma_f32_16x16x32_bf16 v[106:109], v[166:169], v[198:201], v[106:109]
	v_mfma_f32_16x16x32_bf16 v[94:97], v[158:161], v[206:209], v[94:97]
	v_mfma_f32_16x16x32_bf16 v[90:93], v[166:169], v[206:209], v[90:93]
	v_mfma_f32_16x16x32_bf16 v[78:81], v[158:161], v[214:217], v[78:81]
	v_mfma_f32_16x16x32_bf16 v[74:77], v[166:169], v[214:217], v[74:77]
	v_mfma_f32_16x16x32_bf16 v[118:121], v[170:173], v[186:189], v[118:121]
	v_mfma_f32_16x16x32_bf16 v[114:117], v[178:181], v[186:189], v[114:117]
	v_mfma_f32_16x16x32_bf16 v[102:105], v[170:173], v[194:197], v[102:105]
	v_mfma_f32_16x16x32_bf16 v[98:101], v[178:181], v[194:197], v[98:101]
	v_mfma_f32_16x16x32_bf16 v[86:89], v[170:173], v[202:205], v[86:89]
	v_mfma_f32_16x16x32_bf16 v[82:85], v[178:181], v[202:205], v[82:85]
	v_mfma_f32_16x16x32_bf16 v[70:73], v[170:173], v[210:213], v[70:73]
	v_mfma_f32_16x16x32_bf16 v[66:69], v[178:181], v[210:213], v[66:69]
	v_mfma_f32_16x16x32_bf16 v[118:121], v[174:177], v[190:193], v[118:121]
	v_mfma_f32_16x16x32_bf16 v[114:117], v[182:185], v[190:193], v[114:117]
	v_mfma_f32_16x16x32_bf16 v[102:105], v[174:177], v[198:201], v[102:105]
	v_mfma_f32_16x16x32_bf16 v[98:101], v[182:185], v[198:201], v[98:101]
	v_mfma_f32_16x16x32_bf16 v[86:89], v[174:177], v[206:209], v[86:89]
	v_mfma_f32_16x16x32_bf16 v[82:85], v[182:185], v[206:209], v[82:85]
	v_mfma_f32_16x16x32_bf16 v[70:73], v[174:177], v[214:217], v[70:73]
	v_mfma_f32_16x16x32_bf16 v[66:69], v[182:185], v[214:217], v[66:69]
	s_barrier
	s_add_i32 s62, s57, s30
	v_lshl_add_u64 v[150:151], s[40:41], 0, v[132:133]
	s_mov_b32 m0, s62
	ds_read_b128 v[186:189], v156 offset:16384
	ds_read_b128 v[190:193], v156 offset:17408
	ds_read_b128 v[194:197], v156 offset:18432
	ds_read_b128 v[198:201], v156 offset:19456
	ds_read_b128 v[202:205], v156 offset:20480
	ds_read_b128 v[206:209], v156 offset:21504
	ds_read_b128 v[210:213], v156 offset:22528
	ds_read_b128 v[214:217], v156 offset:23552
	global_load_lds_dwordx4 v132, s[40:41]
	s_add_i32 m0, s62, 0x2000
	s_add_u32 s62, s40, 0x10000
	v_lshl_add_u64 v[218:219], s[40:41], 0, v[136:137]
	s_addc_u32 s63, s41, 0
	s_add_i32 s64, s58, s30
	global_load_lds_dwordx4 v136, s[40:41]
	s_mov_b32 m0, s64
	v_lshl_add_u64 v[222:223], s[42:43], 0, v[134:135]
	global_load_lds_dwordx4 v132, s[62:63]
	s_add_i32 m0, s64, 0x2000
	s_nop 0
	global_load_lds_dwordx4 v136, s[62:63]
	v_lshl_add_u64 v[220:221], s[42:43], 0, v[130:131]
	s_mov_b32 m0, s31
	s_nop 0
	global_load_lds_dwordx4 v130, s[42:43]
	s_mov_b32 m0, s33
	s_nop 0
	global_load_lds_dwordx4 v134, s[42:43]
	s_waitcnt vmcnt(8)
	s_waitcnt lgkmcnt(0)
	s_barrier
; #define PG8_STAGE(bufoff, gbase, voff) do { _Pragma("unroll") for (int _i = 0; _i < 2; ++_i) \
;         __builtin_amdgcn_global_load_lds((const unsigned*)((const char*)(gbase) + (voff)[_i]), (PG8_LAS unsigned*)(lds + (bufoff) + ldsw + _i * 8192), 16, 0, 0); } while (0)
; #define PG8_LDA(dst, b, h) do { _Pragma("unroll") for (int m = 0; m < 4; ++m) _Pragma("unroll") for (int k = 0; k < 2; ++k) dst[m][k] = *(const PG8_LAS bf16x8*)(lds + PG8_SA(b, h) + aoff + m * 2048 + k * 1024); } while (0)
; #define PG8_LDB(dst, b, h) do { _Pragma("unroll") for (int n = 0; n < 2; ++n) _Pragma("unroll") for (int k = 0; k < 2; ++k) dst[n][k] = *(const PG8_LAS bf16x8*)(lds + PG8_SB(b, h) + boff + n * 2048 + k * 1024); } while (0)
; #define PG8_MMA(ai, bj, At, Bt) do { __builtin_amdgcn_s_setprio(1); _Pragma("unroll") for (int m = 0; m < 4; ++m) _Pragma("unroll") for (int n = 0; n < 2; ++n) _Pragma("unroll") for (int k = 0; k < 2; ++k) \
;         acc[ai][bj][m][n] = __builtin_amdgcn_mfma_f32_16x16x32_bf16(Bt[n][k], At[m][k], acc[ai][bj][m][n], 0, 0, 0); __builtin_amdgcn_s_setprio(0); } while (0)
; #define PG8_WAIT_V(n) asm volatile("s_waitcnt vmcnt(" #n ")" ::: "memory")
; #define PG8_WAIT_L(n) asm volatile("s_waitcnt lgkmcnt(" #n ")" ::: "memory")
; #define PG8_BAR __builtin_amdgcn_s_barrier()
; #define PG8_SCHED __builtin_amdgcn_sched_barrier(0)
; template <class Epi, class Sched, bool ALIGN_EPI = false, bool SP2 = false>
; __device__ __forceinline__ void gemm_phase(PG8_LAS unsigned char* lds, const Gemm g, const Sched& S, const Epi& E) {
;     ...
;             PG8_WAIT_V(8); PG8_WAIT_L(0); PG8_BAR; PG8_MMA(1, 0, At, B0); PG8_MMA(1, 1, At, B1); PG8_BAR; PG8_SCHED;
;             PG8_LDB(B0, 1, 0); PG8_LDB(B1, 1, 1); PG8_SCHED; PG8_LDA(At, 1, 0); PG8_STAGE(PG8_SA(0, 1), a2 + hstep, voffA);
;             PG8_WAIT_V(8); PG8_WAIT_L(0); PG8_BAR; PG8_MMA(0, 0, At, B0); PG8_MMA(0, 1, At, B1); PG8_BAR; PG8_SCHED;
	v_mfma_f32_16x16x32_bf16 v[62:65], v[146:149], v[186:189], v[62:65]
	v_mfma_f32_16x16x32_bf16 v[58:61], v[162:165], v[186:189], v[58:61]
	v_mfma_f32_16x16x32_bf16 v[46:49], v[146:149], v[194:197], v[46:49]
	v_mfma_f32_16x16x32_bf16 v[42:45], v[162:165], v[194:197], v[42:45]
	v_mfma_f32_16x16x32_bf16 v[30:33], v[146:149], v[202:205], v[30:33]
	v_mfma_f32_16x16x32_bf16 v[26:29], v[162:165], v[202:205], v[26:29]
	v_mfma_f32_16x16x32_bf16 v[14:17], v[146:149], v[210:213], v[14:17]
	v_mfma_f32_16x16x32_bf16 v[10:13], v[162:165], v[210:213], v[10:13]
	v_mfma_f32_16x16x32_bf16 v[62:65], v[158:161], v[190:193], v[62:65]
	v_mfma_f32_16x16x32_bf16 v[58:61], v[166:169], v[190:193], v[58:61]
	v_mfma_f32_16x16x32_bf16 v[46:49], v[158:161], v[198:201], v[46:49]
	v_mfma_f32_16x16x32_bf16 v[42:45], v[166:169], v[198:201], v[42:45]
	v_mfma_f32_16x16x32_bf16 v[30:33], v[158:161], v[206:209], v[30:33]
	v_mfma_f32_16x16x32_bf16 v[26:29], v[166:169], v[206:209], v[26:29]
	v_mfma_f32_16x16x32_bf16 v[14:17], v[158:161], v[214:217], v[14:17]
	v_mfma_f32_16x16x32_bf16 v[10:13], v[166:169], v[214:217], v[10:13]
	v_mfma_f32_16x16x32_bf16 v[54:57], v[170:173], v[186:189], v[54:57]
	v_mfma_f32_16x16x32_bf16 v[50:53], v[178:181], v[186:189], v[50:53]
	v_mfma_f32_16x16x32_bf16 v[38:41], v[170:173], v[194:197], v[38:41]
	v_mfma_f32_16x16x32_bf16 v[34:37], v[178:181], v[194:197], v[34:37]
	v_mfma_f32_16x16x32_bf16 v[22:25], v[170:173], v[202:205], v[22:25]
	v_mfma_f32_16x16x32_bf16 v[18:21], v[178:181], v[202:205], v[18:21]
	v_mfma_f32_16x16x32_bf16 v[6:9], v[170:173], v[210:213], v[6:9]
	v_mfma_f32_16x16x32_bf16 v[2:5], v[178:181], v[210:213], v[2:5]
	v_mfma_f32_16x16x32_bf16 v[54:57], v[174:177], v[190:193], v[54:57]
	v_mfma_f32_16x16x32_bf16 v[50:53], v[182:185], v[190:193], v[50:53]
	v_mfma_f32_16x16x32_bf16 v[38:41], v[174:177], v[198:201], v[38:41]
	v_mfma_f32_16x16x32_bf16 v[34:37], v[182:185], v[198:201], v[34:37]
	v_mfma_f32_16x16x32_bf16 v[22:25], v[174:177], v[206:209], v[22:25]
	v_mfma_f32_16x16x32_bf16 v[18:21], v[182:185], v[206:209], v[18:21]
	v_mfma_f32_16x16x32_bf16 v[6:9], v[174:177], v[214:217], v[6:9]
	v_mfma_f32_16x16x32_bf16 v[2:5], v[182:185], v[214:217], v[2:5]
	s_barrier
	s_add_i32 s62, 0, 0x18000
	v_add_u32_e32 v157, s62, v152
	s_add_i32 s63, 0, 0x1c000
	ds_read_b128 v[146:149], v157
	ds_read_b128 v[158:161], v157 offset:1024
	ds_read_b128 v[162:165], v157 offset:2048
	ds_read_b128 v[166:169], v157 offset:3072
	v_add_u32_e32 v157, s63, v152
	ds_read_b128 v[170:173], v157
	ds_read_b128 v[174:177], v157 offset:1024
	ds_read_b128 v[178:181], v157 offset:2048
	ds_read_b128 v[182:185], v157 offset:3072
	s_add_u32 s42, s42, 0x40000
	s_addc_u32 s43, s43, 0
	s_mov_b32 m0, s44
	ds_read_b128 v[186:189], v156 offset:32768
	ds_read_b128 v[190:193], v156 offset:33792
	ds_read_b128 v[194:197], v156 offset:34816
	ds_read_b128 v[198:201], v156 offset:35840
	ds_read_b128 v[202:205], v156 offset:36864
	ds_read_b128 v[206:209], v156 offset:37888
	ds_read_b128 v[210:213], v156 offset:38912
	ds_read_b128 v[214:217], v156 offset:39936
	global_load_lds_dwordx4 v130, s[42:43]
	s_mov_b32 m0, s45
	s_nop 0
	global_load_lds_dwordx4 v134, s[42:43]
	s_waitcnt vmcnt(8)
	s_waitcnt lgkmcnt(0)
	s_barrier
	v_mfma_f32_16x16x32_bf16 v[126:129], v[146:149], v[186:189], v[126:129]
	v_mfma_f32_16x16x32_bf16 v[122:125], v[162:165], v[186:189], v[122:125]
	v_mfma_f32_16x16x32_bf16 v[110:113], v[146:149], v[194:197], v[110:113]
	v_mfma_f32_16x16x32_bf16 v[106:109], v[162:165], v[194:197], v[106:109]
	v_mfma_f32_16x16x32_bf16 v[94:97], v[146:149], v[202:205], v[94:97]
	v_mfma_f32_16x16x32_bf16 v[90:93], v[162:165], v[202:205], v[90:93]
	v_mfma_f32_16x16x32_bf16 v[78:81], v[146:149], v[210:213], v[78:81]
	v_mfma_f32_16x16x32_bf16 v[74:77], v[162:165], v[210:213], v[74:77]
	v_mfma_f32_16x16x32_bf16 v[126:129], v[158:161], v[190:193], v[126:129]
	v_mfma_f32_16x16x32_bf16 v[122:125], v[166:169], v[190:193], v[122:125]
	v_mfma_f32_16x16x32_bf16 v[110:113], v[158:161], v[198:201], v[110:113]
	v_mfma_f32_16x16x32_bf16 v[106:109], v[166:169], v[198:201], v[106:109]
	v_mfma_f32_16x16x32_bf16 v[94:97], v[158:161], v[206:209], v[94:97]
	v_mfma_f32_16x16x32_bf16 v[90:93], v[166:169], v[206:209], v[90:93]
	v_mfma_f32_16x16x32_bf16 v[78:81], v[158:161], v[214:217], v[78:81]
	v_mfma_f32_16x16x32_bf16 v[74:77], v[166:169], v[214:217], v[74:77]
	v_mfma_f32_16x16x32_bf16 v[118:121], v[170:173], v[186:189], v[118:121]
	v_mfma_f32_16x16x32_bf16 v[114:117], v[178:181], v[186:189], v[114:117]
	v_mfma_f32_16x16x32_bf16 v[102:105], v[170:173], v[194:197], v[102:105]
	v_mfma_f32_16x16x32_bf16 v[98:101], v[178:181], v[194:197], v[98:101]
	v_mfma_f32_16x16x32_bf16 v[86:89], v[170:173], v[202:205], v[86:89]
	v_mfma_f32_16x16x32_bf16 v[82:85], v[178:181], v[202:205], v[82:85]
	v_mfma_f32_16x16x32_bf16 v[70:73], v[170:173], v[210:213], v[70:73]
	v_mfma_f32_16x16x32_bf16 v[66:69], v[178:181], v[210:213], v[66:69]
	v_mfma_f32_16x16x32_bf16 v[118:121], v[174:177], v[190:193], v[118:121]
	v_mfma_f32_16x16x32_bf16 v[114:117], v[182:185], v[190:193], v[114:117]
	v_mfma_f32_16x16x32_bf16 v[102:105], v[174:177], v[198:201], v[102:105]
	v_mfma_f32_16x16x32_bf16 v[98:101], v[182:185], v[198:201], v[98:101]
	v_mfma_f32_16x16x32_bf16 v[86:89], v[174:177], v[206:209], v[86:89]
	v_mfma_f32_16x16x32_bf16 v[82:85], v[182:185], v[206:209], v[82:85]
	v_mfma_f32_16x16x32_bf16 v[70:73], v[174:177], v[214:217], v[70:73]
	v_mfma_f32_16x16x32_bf16 v[66:69], v[182:185], v[214:217], v[66:69]
	s_barrier
; #define PG8_STAGE(bufoff, gbase, voff) do { _Pragma("unroll") for (int _i = 0; _i < 2; ++_i) \
;         __builtin_amdgcn_global_load_lds((const unsigned*)((const char*)(gbase) + (voff)[_i]), (PG8_LAS unsigned*)(lds + (bufoff) + ldsw + _i * 8192), 16, 0, 0); } while (0)
; #define PG8_LDA(dst, b, h) do { _Pragma("unroll") for (int m = 0; m < 4; ++m) _Pragma("unroll") for (int k = 0; k < 2; ++k) dst[m][k] = *(const PG8_LAS bf16x8*)(lds + PG8_SA(b, h) + aoff + m * 2048 + k * 1024); } while (0)
; #define PG8_MMA(ai, bj, At, Bt) do { __builtin_amdgcn_s_setprio(1); _Pragma("unroll") for (int m = 0; m < 4; ++m) _Pragma("unroll") for (int n = 0; n < 2; ++n) _Pragma("unroll") for (int k = 0; k < 2; ++k) \
;         acc[ai][bj][m][n] = __builtin_amdgcn_mfma_f32_16x16x32_bf16(Bt[n][k], At[m][k], acc[ai][bj][m][n], 0, 0, 0); __builtin_amdgcn_s_setprio(0); } while (0)
; #define PG8_WAIT_V(n) asm volatile("s_waitcnt vmcnt(" #n ")" ::: "memory")
; #define PG8_WAIT_L(n) asm volatile("s_waitcnt lgkmcnt(" #n ")" ::: "memory")
; #define PG8_BAR __builtin_amdgcn_s_barrier()
; #define PG8_SCHED __builtin_amdgcn_sched_barrier(0)
; template <class Epi, class Sched, bool ALIGN_EPI = false, bool SP2 = false>
; __device__ __forceinline__ void gemm_phase(PG8_LAS unsigned char* lds, const Gemm g, const Sched& S, const Epi& E) {
;     ...
;             PG8_LDA(At, 1, 1); PG8_STAGE(PG8_SB(1, 0), b3, voffB); PG8_STAGE(PG8_SB(1, 1), b3 + hstepB, voffB); PG8_STAGE(PG8_SA(1, 0), a3, voffA);
;             PG8_WAIT_V(8); PG8_WAIT_L(0); PG8_BAR; PG8_MMA(1, 0, At, B0); PG8_MMA(1, 1, At, B1); PG8_BAR; PG8_SCHED;
	s_add_i32 s42, s62, s30
	v_lshl_add_u64 v[150:151], v[150:151], 0, s[10:11]
	s_mov_b32 m0, s42
	ds_read_b128 v[186:189], v156 offset:49152
	ds_read_b128 v[190:193], v156 offset:50176
	ds_read_b128 v[194:197], v156 offset:51200
	ds_read_b128 v[198:201], v156 offset:52224
	ds_read_b128 v[202:205], v156 offset:53248
	ds_read_b128 v[206:209], v156 offset:54272
	ds_read_b128 v[210:213], v156 offset:55296
	ds_read_b128 v[214:217], v156 offset:56320
	global_load_lds_dwordx4 v[150:151], off
	s_add_i32 m0, s42, 0x2000
	s_add_u32 s40, s40, 0x10080
	v_lshl_add_u64 v[150:151], v[218:219], 0, s[10:11]
	s_addc_u32 s41, s41, 0
	s_add_i32 s42, s63, s30
	global_load_lds_dwordx4 v[150:151], off
	s_mov_b32 m0, s42
	s_nop 0
	global_load_lds_dwordx4 v132, s[40:41]
	s_add_i32 m0, s42, 0x2000
	s_nop 0
	global_load_lds_dwordx4 v136, s[40:41]
	v_lshl_add_u64 v[150:151], v[220:221], 0, s[10:11]
	s_mov_b32 m0, s47
	s_nop 0
	global_load_lds_dwordx4 v[150:151], off
	v_lshl_add_u64 v[150:151], v[222:223], 0, s[10:11]
	s_mov_b32 m0, s54
	s_nop 0
	global_load_lds_dwordx4 v[150:151], off
	s_waitcnt vmcnt(8)
	s_waitcnt lgkmcnt(0)
	s_barrier
	v_mfma_f32_16x16x32_bf16 v[62:65], v[146:149], v[186:189], v[62:65]
	v_mfma_f32_16x16x32_bf16 v[58:61], v[162:165], v[186:189], v[58:61]
	v_mfma_f32_16x16x32_bf16 v[46:49], v[146:149], v[194:197], v[46:49]
	v_mfma_f32_16x16x32_bf16 v[42:45], v[162:165], v[194:197], v[42:45]
	v_mfma_f32_16x16x32_bf16 v[30:33], v[146:149], v[202:205], v[30:33]
	v_mfma_f32_16x16x32_bf16 v[26:29], v[162:165], v[202:205], v[26:29]
	v_mfma_f32_16x16x32_bf16 v[14:17], v[146:149], v[210:213], v[14:17]
	v_mfma_f32_16x16x32_bf16 v[10:13], v[162:165], v[210:213], v[10:13]
	v_mfma_f32_16x16x32_bf16 v[62:65], v[158:161], v[190:193], v[62:65]
	v_mfma_f32_16x16x32_bf16 v[58:61], v[166:169], v[190:193], v[58:61]
	v_mfma_f32_16x16x32_bf16 v[46:49], v[158:161], v[198:201], v[46:49]
	v_mfma_f32_16x16x32_bf16 v[42:45], v[166:169], v[198:201], v[42:45]
	v_mfma_f32_16x16x32_bf16 v[30:33], v[158:161], v[206:209], v[30:33]
	v_mfma_f32_16x16x32_bf16 v[26:29], v[166:169], v[206:209], v[26:29]
	v_mfma_f32_16x16x32_bf16 v[14:17], v[158:161], v[214:217], v[14:17]
	v_mfma_f32_16x16x32_bf16 v[10:13], v[166:169], v[214:217], v[10:13]
	v_mfma_f32_16x16x32_bf16 v[54:57], v[170:173], v[186:189], v[54:57]
	v_mfma_f32_16x16x32_bf16 v[50:53], v[178:181], v[186:189], v[50:53]
	v_mfma_f32_16x16x32_bf16 v[38:41], v[170:173], v[194:197], v[38:41]
	v_mfma_f32_16x16x32_bf16 v[34:37], v[178:181], v[194:197], v[34:37]
	v_mfma_f32_16x16x32_bf16 v[22:25], v[170:173], v[202:205], v[22:25]
	v_mfma_f32_16x16x32_bf16 v[18:21], v[178:181], v[202:205], v[18:21]
	v_mfma_f32_16x16x32_bf16 v[6:9], v[170:173], v[210:213], v[6:9]
	v_mfma_f32_16x16x32_bf16 v[2:5], v[178:181], v[210:213], v[2:5]
	v_mfma_f32_16x16x32_bf16 v[54:57], v[174:177], v[190:193], v[54:57]
	v_mfma_f32_16x16x32_bf16 v[50:53], v[182:185], v[190:193], v[50:53]
	v_mfma_f32_16x16x32_bf16 v[38:41], v[174:177], v[198:201], v[38:41]
	v_mfma_f32_16x16x32_bf16 v[34:37], v[182:185], v[198:201], v[34:37]
	v_mfma_f32_16x16x32_bf16 v[22:25], v[174:177], v[206:209], v[22:25]
	v_mfma_f32_16x16x32_bf16 v[18:21], v[182:185], v[206:209], v[18:21]
	v_mfma_f32_16x16x32_bf16 v[6:9], v[174:177], v[214:217], v[6:9]
	v_mfma_f32_16x16x32_bf16 v[2:5], v[182:185], v[214:217], v[2:5]
	s_barrier
	s_add_i32 s61, s61, 2
	s_add_u32 s38, s38, 0x100
	s_addc_u32 s39, s39, 0
	s_add_u32 s59, s59, 0x100
	s_addc_u32 s60, s60, 0
	s_cmp_gt_u32 s61, 13
	s_cbranch_scc0 .LBB0_1313
	s_and_b64 vcc, exec, s[14:15]
	s_cbranch_vccz .LBB0_1316
	s_barrier

; #define PG8_STAGE(bufoff, gbase, voff) do { _Pragma("unroll") for (int _i = 0; _i < 2; ++_i) \
;         __builtin_amdgcn_global_load_lds((const unsigned*)((const char*)(gbase) + (voff)[_i]), (PG8_LAS unsigned*)(lds + (bufoff) + ldsw + _i * 8192), 16, 0, 0); } while (0)
; #define PG8_LDA(dst, b, h) do { _Pragma("unroll") for (int m = 0; m < 4; ++m) _Pragma("unroll") for (int k = 0; k < 2; ++k) dst[m][k] = *(const PG8_LAS bf16x8*)(lds + PG8_SA(b, h) + aoff + m * 2048 + k * 1024); } while (0)
; #define PG8_LDB(dst, b, h) do { _Pragma("unroll") for (int n = 0; n < 2; ++n) _Pragma("unroll") for (int k = 0; k < 2; ++k) dst[n][k] = *(const PG8_LAS bf16x8*)(lds + PG8_SB(b, h) + boff + n * 2048 + k * 1024); } while (0)
; #define PG8_MMA(ai, bj, At, Bt) do { __builtin_amdgcn_s_setprio(1); _Pragma("unroll") for (int m = 0; m < 4; ++m) _Pragma("unroll") for (int n = 0; n < 2; ++n) _Pragma("unroll") for (int k = 0; k < 2; ++k) \
;         acc[ai][bj][m][n] = __builtin_amdgcn_mfma_f32_16x16x32_bf16(Bt[n][k], At[m][k], acc[ai][bj][m][n], 0, 0, 0); __builtin_amdgcn_s_setprio(0); } while (0)
; #define PG8_WAIT_V(n) asm volatile("s_waitcnt vmcnt(" #n ")" ::: "memory")
; #define PG8_WAIT_L(n) asm volatile("s_waitcnt lgkmcnt(" #n ")" ::: "memory")
; #define PG8_BAR __builtin_amdgcn_s_barrier()
; #define PG8_SCHED __builtin_amdgcn_sched_barrier(0)
; template <class Epi, class Sched, bool ALIGN_EPI = false, bool SP2 = false>
; __device__ __forceinline__ void gemm_phase(PG8_LAS unsigned char* lds, const Gemm g, const Sched& S, const Epi& E) {
;     ...
;             const bool last = (t == nt - 2);
;             const char* a1 = cA + (size_t)(t + 1) * kstep;
;             const char* a2 = last ? nA : cA + (size_t)(t + 2) * kstep; const char* b2 = last ? nB : cB + (size_t)(t + 2) * kstep;
;             const char* a3 = a2 + kstep; const char* b3 = b2 + kstep;
;             if (last && has_next) S.a_ready(nxt);
;             if constexpr (SP2) {
;             PG8_LDB(B0, 0, 0); PG8_LDB(B1, 0, 1); PG8_SCHED; PG8_LDA(At, 0, 0); PG8_STAGE(PG8_SA(1, 1), a1 + hstep, voffA);
;             PG8_WAIT_V(8); PG8_WAIT_L(0); PG8_BAR; PG8_MMA(0, 0, At, B0); PG8_MMA(0, 1, At, B1); PG8_BAR; PG8_SCHED;
;             PG8_LDA(At, 0, 1); PG8_STAGE(PG8_SB(0, 0), b2, voffB); PG8_STAGE(PG8_SB(0, 1), b2 + hstepB, voffB); PG8_STAGE(PG8_SA(0, 0), a2, voffA);
.LBB0_1429:
	v_add_u32_e32 v164, s43, v150
	v_add_u32_e32 v180, s44, v150
	s_add_u32 s26, s8, s24
	ds_read_b128 v[152:155], v164
	ds_read_b128 v[156:159], v164 offset:1024
	ds_read_b128 v[160:163], v164 offset:2048
	ds_read_b128 v[164:167], v164 offset:3072
	ds_read_b128 v[168:171], v180
	ds_read_b128 v[172:175], v180 offset:1024
	ds_read_b128 v[176:179], v180 offset:2048
	ds_read_b128 v[180:183], v180 offset:3072
	s_addc_u32 s27, s9, s25
	s_add_u32 s26, s26, 0x100
	s_addc_u32 s27, s27, 0
	s_add_u32 s55, s21, s24
	s_addc_u32 s56, s45, s25
	s_cmpk_eq_i32 s24, 0x1f00
	s_cselect_b32 s29, s17, s27
	s_cselect_b32 s28, s46, s26
	s_cselect_b32 s27, s15, s56
	s_cselect_b32 s26, s47, s55
	v_lshl_add_u64 v[212:213], v[146:147], 0, s[24:25]
	s_add_i32 m0, s35, 0xc000
	ds_read_b128 v[184:187], v151
	ds_read_b128 v[188:191], v151 offset:1024
	ds_read_b128 v[192:195], v151 offset:2048
	ds_read_b128 v[196:199], v151 offset:3072
	ds_read_b128 v[200:203], v151 offset:4096
	ds_read_b128 v[204:207], v151 offset:5120
	ds_read_b128 v[208:211], v151 offset:6144
	ds_read_b128 v[218:221], v151 offset:7168
	global_load_lds_dwordx4 v[212:213], off
	v_lshl_add_u64 v[212:213], v[148:149], 0, s[24:25]
	s_add_i32 m0, s35, 0xe000
	s_nop 0
	global_load_lds_dwordx4 v[212:213], off
	s_waitcnt vmcnt(8)
	s_waitcnt lgkmcnt(0)
	s_barrier
	v_mfma_f32_16x16x32_bf16 v[126:129], v[152:155], v[184:187], v[126:129]
	v_mfma_f32_16x16x32_bf16 v[122:125], v[160:163], v[184:187], v[122:125]
	v_mfma_f32_16x16x32_bf16 v[110:113], v[152:155], v[192:195], v[110:113]
	v_mfma_f32_16x16x32_bf16 v[106:109], v[160:163], v[192:195], v[106:109]
	v_mfma_f32_16x16x32_bf16 v[94:97], v[152:155], v[200:203], v[94:97]
	v_mfma_f32_16x16x32_bf16 v[90:93], v[160:163], v[200:203], v[90:93]
	v_mfma_f32_16x16x32_bf16 v[78:81], v[152:155], v[208:211], v[78:81]
	v_mfma_f32_16x16x32_bf16 v[74:77], v[160:163], v[208:211], v[74:77]
	v_mfma_f32_16x16x32_bf16 v[126:129], v[156:159], v[188:191], v[126:129]
	v_mfma_f32_16x16x32_bf16 v[122:125], v[164:167], v[188:191], v[122:125]
	v_mfma_f32_16x16x32_bf16 v[110:113], v[156:159], v[196:199], v[110:113]
	v_mfma_f32_16x16x32_bf16 v[106:109], v[164:167], v[196:199], v[106:109]
	v_mfma_f32_16x16x32_bf16 v[94:97], v[156:159], v[204:207], v[94:97]
	v_mfma_f32_16x16x32_bf16 v[90:93], v[164:167], v[204:207], v[90:93]
	v_mfma_f32_16x16x32_bf16 v[78:81], v[156:159], v[218:221], v[78:81]
	v_mfma_f32_16x16x32_bf16 v[74:77], v[164:167], v[218:221], v[74:77]
	v_mfma_f32_16x16x32_bf16 v[118:121], v[168:171], v[184:187], v[118:121]
	v_mfma_f32_16x16x32_bf16 v[114:117], v[176:179], v[184:187], v[114:117]
	v_mfma_f32_16x16x32_bf16 v[102:105], v[168:171], v[192:195], v[102:105]
	v_mfma_f32_16x16x32_bf16 v[98:101], v[176:179], v[192:195], v[98:101]
	v_mfma_f32_16x16x32_bf16 v[86:89], v[168:171], v[200:203], v[86:89]
	v_mfma_f32_16x16x32_bf16 v[82:85], v[176:179], v[200:203], v[82:85]
	v_mfma_f32_16x16x32_bf16 v[70:73], v[168:171], v[208:211], v[70:73]
	v_mfma_f32_16x16x32_bf16 v[66:69], v[176:179], v[208:211], v[66:69]
	v_mfma_f32_16x16x32_bf16 v[118:121], v[172:175], v[188:191], v[118:121]
	v_mfma_f32_16x16x32_bf16 v[114:117], v[180:183], v[188:191], v[114:117]
	v_mfma_f32_16x16x32_bf16 v[102:105], v[172:175], v[196:199], v[102:105]
	v_mfma_f32_16x16x32_bf16 v[98:101], v[180:183], v[196:199], v[98:101]
	v_mfma_f32_16x16x32_bf16 v[86:89], v[172:175], v[204:207], v[86:89]
	v_mfma_f32_16x16x32_bf16 v[82:85], v[180:183], v[204:207], v[82:85]
	v_mfma_f32_16x16x32_bf16 v[70:73], v[172:175], v[218:221], v[70:73]
	v_mfma_f32_16x16x32_bf16 v[66:69], v[180:183], v[218:221], v[66:69]
	s_barrier
	s_add_i32 s55, s43, s34
	v_lshl_add_u64 v[212:213], s[26:27], 0, v[132:133]
	s_mov_b32 m0, s55
	ds_read_b128 v[184:187], v151 offset:16384
	ds_read_b128 v[188:191], v151 offset:17408
	ds_read_b128 v[192:195], v151 offset:18432
	ds_read_b128 v[196:199], v151 offset:19456
	ds_read_b128 v[200:203], v151 offset:20480
	ds_read_b128 v[204:207], v151 offset:21504
	ds_read_b128 v[208:211], v151 offset:22528
	ds_read_b128 v[218:221], v151 offset:23552
	global_load_lds_dwordx4 v132, s[26:27]
	s_add_i32 m0, s55, 0x2000
	s_add_u32 s56, s26, 0x40000
	v_lshl_add_u64 v[222:223], s[26:27], 0, v[136:137]
	s_addc_u32 s57, s27, 0
	s_add_i32 s55, s44, s34
	global_load_lds_dwordx4 v136, s[26:27]
	s_mov_b32 m0, s55
	v_lshl_add_u64 v[226:227], s[28:29], 0, v[134:135]
	global_load_lds_dwordx4 v132, s[56:57]
	s_add_i32 m0, s55, 0x2000
	s_nop 0
	global_load_lds_dwordx4 v136, s[56:57]
	v_lshl_add_u64 v[224:225], s[28:29], 0, v[130:131]
	s_mov_b32 m0, s35
	s_nop 0
	global_load_lds_dwordx4 v130, s[28:29]
	s_mov_b32 m0, s36
	s_nop 0
	global_load_lds_dwordx4 v134, s[28:29]
	s_waitcnt vmcnt(8)
	s_waitcnt lgkmcnt(0)
	s_barrier
; #define PG8_STAGE(bufoff, gbase, voff) do { _Pragma("unroll") for (int _i = 0; _i < 2; ++_i) \
;         __builtin_amdgcn_global_load_lds((const unsigned*)((const char*)(gbase) + (voff)[_i]), (PG8_LAS unsigned*)(lds + (bufoff) + ldsw + _i * 8192), 16, 0, 0); } while (0)
; #define PG8_LDA(dst, b, h) do { _Pragma("unroll") for (int m = 0; m < 4; ++m) _Pragma("unroll") for (int k = 0; k < 2; ++k) dst[m][k] = *(const PG8_LAS bf16x8*)(lds + PG8_SA(b, h) + aoff + m * 2048 + k * 1024); } while (0)
; #define PG8_LDB(dst, b, h) do { _Pragma("unroll") for (int n = 0; n < 2; ++n) _Pragma("unroll") for (int k = 0; k < 2; ++k) dst[n][k] = *(const PG8_LAS bf16x8*)(lds + PG8_SB(b, h) + boff + n * 2048 + k * 1024); } while (0)
; #define PG8_MMA(ai, bj, At, Bt) do { __builtin_amdgcn_s_setprio(1); _Pragma("unroll") for (int m = 0; m < 4; ++m) _Pragma("unroll") for (int n = 0; n < 2; ++n) _Pragma("unroll") for (int k = 0; k < 2; ++k) \
;         acc[ai][bj][m][n] = __builtin_amdgcn_mfma_f32_16x16x32_bf16(Bt[n][k], At[m][k], acc[ai][bj][m][n], 0, 0, 0); __builtin_amdgcn_s_setprio(0); } while (0)
; #define PG8_WAIT_V(n) asm volatile("s_waitcnt vmcnt(" #n ")" ::: "memory")
; #define PG8_WAIT_L(n) asm volatile("s_waitcnt lgkmcnt(" #n ")" ::: "memory")
; #define PG8_BAR __builtin_amdgcn_s_barrier()
; #define PG8_SCHED __builtin_amdgcn_sched_barrier(0)
; template <class Epi, class Sched, bool ALIGN_EPI = false, bool SP2 = false>
; __device__ __forceinline__ void gemm_phase(PG8_LAS unsigned char* lds, const Gemm g, const Sched& S, const Epi& E) {
;     ...
;             PG8_WAIT_V(8); PG8_WAIT_L(0); PG8_BAR; PG8_MMA(1, 0, At, B0); PG8_MMA(1, 1, At, B1); PG8_BAR; PG8_SCHED;
;             PG8_LDB(B0, 1, 0); PG8_LDB(B1, 1, 1); PG8_SCHED; PG8_LDA(At, 1, 0); PG8_STAGE(PG8_SA(0, 1), a2 + hstep, voffA);
;             PG8_WAIT_V(8); PG8_WAIT_L(0); PG8_BAR; PG8_MMA(0, 0, At, B0); PG8_MMA(0, 1, At, B1); PG8_BAR; PG8_SCHED;
	v_mfma_f32_16x16x32_bf16 v[62:65], v[152:155], v[184:187], v[62:65]
	v_mfma_f32_16x16x32_bf16 v[58:61], v[160:163], v[184:187], v[58:61]
	v_mfma_f32_16x16x32_bf16 v[46:49], v[152:155], v[192:195], v[46:49]
	v_mfma_f32_16x16x32_bf16 v[42:45], v[160:163], v[192:195], v[42:45]
	v_mfma_f32_16x16x32_bf16 v[30:33], v[152:155], v[200:203], v[30:33]
	v_mfma_f32_16x16x32_bf16 v[26:29], v[160:163], v[200:203], v[26:29]
	v_mfma_f32_16x16x32_bf16 v[14:17], v[152:155], v[208:211], v[14:17]
	v_mfma_f32_16x16x32_bf16 v[10:13], v[160:163], v[208:211], v[10:13]
	v_mfma_f32_16x16x32_bf16 v[62:65], v[156:159], v[188:191], v[62:65]
	v_mfma_f32_16x16x32_bf16 v[58:61], v[164:167], v[188:191], v[58:61]
	v_mfma_f32_16x16x32_bf16 v[46:49], v[156:159], v[196:199], v[46:49]
	v_mfma_f32_16x16x32_bf16 v[42:45], v[164:167], v[196:199], v[42:45]
	v_mfma_f32_16x16x32_bf16 v[30:33], v[156:159], v[204:207], v[30:33]
	v_mfma_f32_16x16x32_bf16 v[26:29], v[164:167], v[204:207], v[26:29]
	v_mfma_f32_16x16x32_bf16 v[14:17], v[156:159], v[218:221], v[14:17]
	v_mfma_f32_16x16x32_bf16 v[10:13], v[164:167], v[218:221], v[10:13]
	v_mfma_f32_16x16x32_bf16 v[54:57], v[168:171], v[184:187], v[54:57]
	v_mfma_f32_16x16x32_bf16 v[50:53], v[176:179], v[184:187], v[50:53]
	v_mfma_f32_16x16x32_bf16 v[38:41], v[168:171], v[192:195], v[38:41]
	v_mfma_f32_16x16x32_bf16 v[34:37], v[176:179], v[192:195], v[34:37]
	v_mfma_f32_16x16x32_bf16 v[22:25], v[168:171], v[200:203], v[22:25]
	v_mfma_f32_16x16x32_bf16 v[18:21], v[176:179], v[200:203], v[18:21]
	v_mfma_f32_16x16x32_bf16 v[6:9], v[168:171], v[208:211], v[6:9]
	v_mfma_f32_16x16x32_bf16 v[2:5], v[176:179], v[208:211], v[2:5]
	v_mfma_f32_16x16x32_bf16 v[54:57], v[172:175], v[188:191], v[54:57]
	v_mfma_f32_16x16x32_bf16 v[50:53], v[180:183], v[188:191], v[50:53]
	v_mfma_f32_16x16x32_bf16 v[38:41], v[172:175], v[196:199], v[38:41]
	v_mfma_f32_16x16x32_bf16 v[34:37], v[180:183], v[196:199], v[34:37]
	v_mfma_f32_16x16x32_bf16 v[22:25], v[172:175], v[204:207], v[22:25]
	v_mfma_f32_16x16x32_bf16 v[18:21], v[180:183], v[204:207], v[18:21]
	v_mfma_f32_16x16x32_bf16 v[6:9], v[172:175], v[218:221], v[6:9]
	v_mfma_f32_16x16x32_bf16 v[2:5], v[180:183], v[218:221], v[2:5]
	s_barrier
	s_add_i32 s55, 0, 0x18000
	s_add_i32 s56, 0, 0x1c000
	v_add_u32_e32 v164, s55, v150
	v_add_u32_e32 v180, s56, v150
	ds_read_b128 v[152:155], v164
	ds_read_b128 v[156:159], v164 offset:1024
	ds_read_b128 v[160:163], v164 offset:2048
	ds_read_b128 v[164:167], v164 offset:3072
	ds_read_b128 v[168:171], v180
	ds_read_b128 v[172:175], v180 offset:1024
	ds_read_b128 v[176:179], v180 offset:2048
	ds_read_b128 v[180:183], v180 offset:3072
	s_add_u32 s28, s28, 0x100000
	s_addc_u32 s29, s29, 0
	s_mov_b32 m0, s37
	ds_read_b128 v[184:187], v151 offset:32768
	ds_read_b128 v[188:191], v151 offset:33792
	ds_read_b128 v[192:195], v151 offset:34816
	ds_read_b128 v[196:199], v151 offset:35840
	ds_read_b128 v[200:203], v151 offset:36864
	ds_read_b128 v[204:207], v151 offset:37888
	ds_read_b128 v[208:211], v151 offset:38912
	ds_read_b128 v[218:221], v151 offset:39936
	global_load_lds_dwordx4 v130, s[28:29]
	s_mov_b32 m0, s39
	s_nop 0
	global_load_lds_dwordx4 v134, s[28:29]
	s_waitcnt vmcnt(8)
	s_waitcnt lgkmcnt(0)
	s_barrier
	v_mfma_f32_16x16x32_bf16 v[126:129], v[152:155], v[184:187], v[126:129]
	v_mfma_f32_16x16x32_bf16 v[122:125], v[160:163], v[184:187], v[122:125]
	v_mfma_f32_16x16x32_bf16 v[110:113], v[152:155], v[192:195], v[110:113]
	v_mfma_f32_16x16x32_bf16 v[106:109], v[160:163], v[192:195], v[106:109]
	v_mfma_f32_16x16x32_bf16 v[94:97], v[152:155], v[200:203], v[94:97]
	v_mfma_f32_16x16x32_bf16 v[90:93], v[160:163], v[200:203], v[90:93]
	v_mfma_f32_16x16x32_bf16 v[78:81], v[152:155], v[208:211], v[78:81]
	v_mfma_f32_16x16x32_bf16 v[74:77], v[160:163], v[208:211], v[74:77]
	v_mfma_f32_16x16x32_bf16 v[126:129], v[156:159], v[188:191], v[126:129]
	v_mfma_f32_16x16x32_bf16 v[122:125], v[164:167], v[188:191], v[122:125]
	v_mfma_f32_16x16x32_bf16 v[110:113], v[156:159], v[196:199], v[110:113]
	v_mfma_f32_16x16x32_bf16 v[106:109], v[164:167], v[196:199], v[106:109]
	v_mfma_f32_16x16x32_bf16 v[94:97], v[156:159], v[204:207], v[94:97]
	v_mfma_f32_16x16x32_bf16 v[90:93], v[164:167], v[204:207], v[90:93]
	v_mfma_f32_16x16x32_bf16 v[78:81], v[156:159], v[218:221], v[78:81]
	v_mfma_f32_16x16x32_bf16 v[74:77], v[164:167], v[218:221], v[74:77]
	v_mfma_f32_16x16x32_bf16 v[118:121], v[168:171], v[184:187], v[118:121]
	v_mfma_f32_16x16x32_bf16 v[114:117], v[176:179], v[184:187], v[114:117]
	v_mfma_f32_16x16x32_bf16 v[102:105], v[168:171], v[192:195], v[102:105]
	v_mfma_f32_16x16x32_bf16 v[98:101], v[176:179], v[192:195], v[98:101]
	v_mfma_f32_16x16x32_bf16 v[86:89], v[168:171], v[200:203], v[86:89]
	v_mfma_f32_16x16x32_bf16 v[82:85], v[176:179], v[200:203], v[82:85]
	v_mfma_f32_16x16x32_bf16 v[70:73], v[168:171], v[208:211], v[70:73]
	v_mfma_f32_16x16x32_bf16 v[66:69], v[176:179], v[208:211], v[66:69]
	v_mfma_f32_16x16x32_bf16 v[118:121], v[172:175], v[188:191], v[118:121]
	v_mfma_f32_16x16x32_bf16 v[114:117], v[180:183], v[188:191], v[114:117]
	v_mfma_f32_16x16x32_bf16 v[102:105], v[172:175], v[196:199], v[102:105]
	v_mfma_f32_16x16x32_bf16 v[98:101], v[180:183], v[196:199], v[98:101]
	v_mfma_f32_16x16x32_bf16 v[86:89], v[172:175], v[204:207], v[86:89]
	v_mfma_f32_16x16x32_bf16 v[82:85], v[180:183], v[204:207], v[82:85]
	v_mfma_f32_16x16x32_bf16 v[70:73], v[172:175], v[218:221], v[70:73]
	v_mfma_f32_16x16x32_bf16 v[66:69], v[180:183], v[218:221], v[66:69]
	s_barrier
; #define PG8_STAGE(bufoff, gbase, voff) do { _Pragma("unroll") for (int _i = 0; _i < 2; ++_i) \
;         __builtin_amdgcn_global_load_lds((const unsigned*)((const char*)(gbase) + (voff)[_i]), (PG8_LAS unsigned*)(lds + (bufoff) + ldsw + _i * 8192), 16, 0, 0); } while (0)
; #define PG8_LDA(dst, b, h) do { _Pragma("unroll") for (int m = 0; m < 4; ++m) _Pragma("unroll") for (int k = 0; k < 2; ++k) dst[m][k] = *(const PG8_LAS bf16x8*)(lds + PG8_SA(b, h) + aoff + m * 2048 + k * 1024); } while (0)
; #define PG8_MMA(ai, bj, At, Bt) do { __builtin_amdgcn_s_setprio(1); _Pragma("unroll") for (int m = 0; m < 4; ++m) _Pragma("unroll") for (int n = 0; n < 2; ++n) _Pragma("unroll") for (int k = 0; k < 2; ++k) \
;         acc[ai][bj][m][n] = __builtin_amdgcn_mfma_f32_16x16x32_bf16(Bt[n][k], At[m][k], acc[ai][bj][m][n], 0, 0, 0); __builtin_amdgcn_s_setprio(0); } while (0)
; #define PG8_WAIT_V(n) asm volatile("s_waitcnt vmcnt(" #n ")" ::: "memory")
; #define PG8_WAIT_L(n) asm volatile("s_waitcnt lgkmcnt(" #n ")" ::: "memory")
; #define PG8_BAR __builtin_amdgcn_s_barrier()
; #define PG8_SCHED __builtin_amdgcn_sched_barrier(0)
; template <class Epi, class Sched, bool ALIGN_EPI = false, bool SP2 = false>
; __device__ __forceinline__ void gemm_phase(PG8_LAS unsigned char* lds, const Gemm g, const Sched& S, const Epi& E) {
;     ...
;             PG8_LDA(At, 1, 1); PG8_STAGE(PG8_SB(1, 0), b3, voffB); PG8_STAGE(PG8_SB(1, 1), b3 + hstepB, voffB); PG8_STAGE(PG8_SA(1, 0), a3, voffA);
;             PG8_WAIT_V(8); PG8_WAIT_L(0); PG8_BAR; PG8_MMA(1, 0, At, B0); PG8_MMA(1, 1, At, B1); PG8_BAR; PG8_SCHED;
;     ...
;         if (!has_next) break;
; #pragma unroll
;         for (int a = 0; a < 2; ++a)
; #pragma unroll
;             for (int b = 0; b < 2; ++b)
; #pragma unroll
;                 for (int m = 0; m < 4; ++m)
; #pragma unroll
;                     for (int n = 0; n < 2; ++n) acc[a][b][m][n] = (f32x4){0.f, 0.f, 0.f, 0.f};
;         cur = nxt; cA = nA; cB = nB; ++ui;
	s_add_i32 s28, s55, s34
	v_lshl_add_u64 v[212:213], v[212:213], 0, s[10:11]
	s_mov_b32 m0, s28
	ds_read_b128 v[184:187], v151 offset:49152
	ds_read_b128 v[188:191], v151 offset:50176
	ds_read_b128 v[192:195], v151 offset:51200
	ds_read_b128 v[196:199], v151 offset:52224
	ds_read_b128 v[200:203], v151 offset:53248
	ds_read_b128 v[204:207], v151 offset:54272
	ds_read_b128 v[208:211], v151 offset:55296
	ds_read_b128 v[218:221], v151 offset:56320
	global_load_lds_dwordx4 v[212:213], off
	s_add_i32 m0, s28, 0x2000
	s_add_u32 s26, s26, 0x40080
	v_lshl_add_u64 v[212:213], v[222:223], 0, s[10:11]
	s_addc_u32 s27, s27, 0
	s_add_i32 s28, s56, s34
	global_load_lds_dwordx4 v[212:213], off
	s_mov_b32 m0, s28
	s_nop 0
	global_load_lds_dwordx4 v132, s[26:27]
	s_add_i32 m0, s28, 0x2000
	s_nop 0
	global_load_lds_dwordx4 v136, s[26:27]
	v_lshl_add_u64 v[212:213], v[224:225], 0, s[10:11]
	s_mov_b32 m0, s40
	s_nop 0
	global_load_lds_dwordx4 v[212:213], off
	v_lshl_add_u64 v[212:213], v[226:227], 0, s[10:11]
	s_mov_b32 m0, s41
	s_nop 0
	global_load_lds_dwordx4 v[212:213], off
	s_waitcnt vmcnt(8)
	s_waitcnt lgkmcnt(0)
	s_barrier
	v_mfma_f32_16x16x32_bf16 v[62:65], v[152:155], v[184:187], v[62:65]
	v_mfma_f32_16x16x32_bf16 v[58:61], v[160:163], v[184:187], v[58:61]
	v_mfma_f32_16x16x32_bf16 v[46:49], v[152:155], v[192:195], v[46:49]
	v_mfma_f32_16x16x32_bf16 v[42:45], v[160:163], v[192:195], v[42:45]
	v_mfma_f32_16x16x32_bf16 v[30:33], v[152:155], v[200:203], v[30:33]
	v_mfma_f32_16x16x32_bf16 v[26:29], v[160:163], v[200:203], v[26:29]
	v_mfma_f32_16x16x32_bf16 v[14:17], v[152:155], v[208:211], v[14:17]
	v_mfma_f32_16x16x32_bf16 v[10:13], v[160:163], v[208:211], v[10:13]
	v_mfma_f32_16x16x32_bf16 v[62:65], v[156:159], v[188:191], v[62:65]
	v_mfma_f32_16x16x32_bf16 v[58:61], v[164:167], v[188:191], v[58:61]
	v_mfma_f32_16x16x32_bf16 v[46:49], v[156:159], v[196:199], v[46:49]
	v_mfma_f32_16x16x32_bf16 v[42:45], v[164:167], v[196:199], v[42:45]
	v_mfma_f32_16x16x32_bf16 v[30:33], v[156:159], v[204:207], v[30:33]
	v_mfma_f32_16x16x32_bf16 v[26:29], v[164:167], v[204:207], v[26:29]
	v_mfma_f32_16x16x32_bf16 v[14:17], v[156:159], v[218:221], v[14:17]
	v_mfma_f32_16x16x32_bf16 v[10:13], v[164:167], v[218:221], v[10:13]
	v_mfma_f32_16x16x32_bf16 v[54:57], v[168:171], v[184:187], v[54:57]
	v_mfma_f32_16x16x32_bf16 v[50:53], v[176:179], v[184:187], v[50:53]
	v_mfma_f32_16x16x32_bf16 v[38:41], v[168:171], v[192:195], v[38:41]
	v_mfma_f32_16x16x32_bf16 v[34:37], v[176:179], v[192:195], v[34:37]
	v_mfma_f32_16x16x32_bf16 v[22:25], v[168:171], v[200:203], v[22:25]
	v_mfma_f32_16x16x32_bf16 v[18:21], v[176:179], v[200:203], v[18:21]
	v_mfma_f32_16x16x32_bf16 v[6:9], v[168:171], v[208:211], v[6:9]
	v_mfma_f32_16x16x32_bf16 v[2:5], v[176:179], v[208:211], v[2:5]
	v_mfma_f32_16x16x32_bf16 v[54:57], v[172:175], v[188:191], v[54:57]
	v_mfma_f32_16x16x32_bf16 v[50:53], v[180:183], v[188:191], v[50:53]
	v_mfma_f32_16x16x32_bf16 v[38:41], v[172:175], v[196:199], v[38:41]
	v_mfma_f32_16x16x32_bf16 v[34:37], v[180:183], v[196:199], v[34:37]
	v_mfma_f32_16x16x32_bf16 v[22:25], v[172:175], v[204:207], v[22:25]
	v_mfma_f32_16x16x32_bf16 v[18:21], v[180:183], v[204:207], v[18:21]
	v_mfma_f32_16x16x32_bf16 v[6:9], v[172:175], v[218:221], v[6:9]
	v_mfma_f32_16x16x32_bf16 v[2:5], v[180:183], v[218:221], v[2:5]
	s_barrier
	s_add_i32 s54, s54, 2
	s_add_u32 s24, s24, 0x100
	s_addc_u32 s25, s25, 0
	s_cmp_gt_u32 s54, 61
	s_cbranch_scc0 .LBB0_1429
	s_add_u32 s24, s21, 0xffffff00
	s_addc_u32 s25, s45, -1
	s_andn2_b64 vcc, exec, s[2:3]
	s_cbranch_vccnz .LBB0_1420
	v_mov_b32_e32 v2, 0
	s_mov_b32 s6, s14
	s_mov_b32 s4, s16
	s_mov_b64 s[8:9], s[22:23]
	s_mov_b32 s42, s20
	v_mov_b32_e32 v3, 0
	v_mov_b64_e32 v[4:5], 0
	v_mov_b64_e32 v[6:7], 0
	v_mov_b64_e32 v[8:9], 0
	v_mov_b64_e32 v[18:19], 0
	v_mov_b64_e32 v[20:21], 0
	v_mov_b64_e32 v[22:23], 0
	v_mov_b64_e32 v[24:25], 0
	v_mov_b64_e32 v[34:35], 0
	v_mov_b64_e32 v[36:37], 0
	v_mov_b64_e32 v[38:39], 0
	v_mov_b64_e32 v[40:41], 0
	v_mov_b64_e32 v[50:51], 0
	v_mov_b64_e32 v[52:53], 0
	v_mov_b64_e32 v[54:55], 0
	v_mov_b64_e32 v[56:57], 0
	v_mov_b64_e32 v[10:11], 0
	v_mov_b64_e32 v[12:13], 0
	v_mov_b64_e32 v[14:15], 0
	v_mov_b64_e32 v[16:17], 0
	v_mov_b64_e32 v[26:27], 0
	v_mov_b64_e32 v[28:29], 0
	v_mov_b64_e32 v[30:31], 0
	v_mov_b64_e32 v[32:33], 0
	v_mov_b64_e32 v[42:43], 0
	v_mov_b64_e32 v[44:45], 0
	v_mov_b64_e32 v[46:47], 0
	v_mov_b64_e32 v[48:49], 0
	v_mov_b64_e32 v[58:59], 0
	v_mov_b64_e32 v[60:61], 0
	v_mov_b64_e32 v[62:63], 0
	v_mov_b64_e32 v[64:65], 0
	v_mov_b64_e32 v[66:67], 0
	v_mov_b64_e32 v[68:69], 0
	v_mov_b64_e32 v[70:71], 0
	v_mov_b64_e32 v[72:73], 0
	v_mov_b64_e32 v[82:83], 0
	v_mov_b64_e32 v[84:85], 0
	v_mov_b64_e32 v[86:87], 0
	v_mov_b64_e32 v[88:89], 0
	v_mov_b64_e32 v[98:99], 0
	v_mov_b64_e32 v[100:101], 0
	v_mov_b64_e32 v[102:103], 0
	v_mov_b64_e32 v[104:105], 0
	v_mov_b64_e32 v[114:115], 0
	v_mov_b64_e32 v[116:117], 0
	v_mov_b64_e32 v[118:119], 0
	v_mov_b64_e32 v[120:121], 0
	v_mov_b64_e32 v[74:75], 0
	v_mov_b64_e32 v[76:77], 0
	v_mov_b64_e32 v[78:79], 0
	v_mov_b64_e32 v[80:81], 0
	v_mov_b64_e32 v[90:91], 0
	v_mov_b64_e32 v[92:93], 0
	v_mov_b64_e32 v[94:95], 0
	v_mov_b64_e32 v[96:97], 0
	v_mov_b64_e32 v[106:107], 0
	v_mov_b64_e32 v[108:109], 0
	v_mov_b64_e32 v[110:111], 0
	v_mov_b64_e32 v[112:113], 0
	v_mov_b64_e32 v[122:123], 0
	v_mov_b64_e32 v[124:125], 0
	v_mov_b64_e32 v[126:127], 0
	v_mov_b64_e32 v[128:129], 0
	s_andn2_b64 vcc, exec, s[0:1]
	s_cbranch_vccnz .LBB0_1421
